# v44 (DMA behind MFMAs, late image wait) + context-row norm loops issue all 40 row loads before the X-dependent arithmetic
# speedup vs baseline: 1.0010x; 1.0010x over previous
; __device__ __forceinline__ void norm_load(const bf16_t* xrow, f32x4 (&v)[8], int lane) {
;     const u32x2* xr = (const u32x2*)xrow + lane; u32x2 r[8];
; #pragma unroll
;     for (int j = 0; j < 8; ++j) r[j] = xr[64 * j];
; #pragma unroll
;     for (int j = 0; j < 8; ++j) v[j] = (f32x4){bf_lo(r[j].x), bf_hi(r[j].x), bf_lo(r[j].y), bf_hi(r[j].y)};
; }
; template <int MODE>
; __device__ __forceinline__ void norm_apply(f32x4 (&v)[8], bf16_t* xcopy, const f32x4 (&GG)[8], const f32x4 (&SS)[8], bf16_t* obf, float* of32, int lane, const float* slabrow = nullptr, const float* gate = nullptr) {
;     float ss = 0.f;
;     if (slabrow) {
; #pragma unroll
;         for (int jh = 0; jh < 2; ++jh) { u32x2 p[4][8];
; #pragma unroll
;             for (int jj = 0; jj < 4; ++jj) { const int j = jh * 4 + jj; const u32x2* sp = (const u32x2*)((const bf16_t*)slabrow + (size_t)j * 8 * 65536) + lane;
; #pragma unroll
;                 for (int s = 0; s < 8; ++s) p[jj][s] = sp[(size_t)s * 16384]; }
.LBB9_1331:
	s_ashr_i32 s4, s10, 8
	s_ashr_i32 s5, s4, 31
	s_lshl_b64 s[4:5], s[4:5], 23
	s_add_u32 s1, s22, s4
	s_addc_u32 s3, s23, s5
	s_and_b32 s4, s0, 0xff00
	s_lshl_b32 s4, s4, 1
	s_add_u32 s4, s1, s4
	v_add_co_u32_e32 v78, vcc, 0xfb800000, v76
	s_addc_u32 s5, s3, 0
	s_nop 0
	v_addc_co_u32_e32 v79, vcc, -1, v77, vcc
	v_lshl_add_u64 v[104:105], s[4:5], 0, v[186:187]
	v_add_co_u32_e32 v84, vcc, s56, v104
	global_load_dwordx2 v[108:109], v[78:79], off offset:-3584
	global_load_dwordx2 v[106:107], v[78:79], off offset:-3072
	global_load_dwordx2 v[98:99], v[78:79], off offset:-2560
	global_load_dwordx2 v[96:97], v[78:79], off offset:-2048
	global_load_dwordx2 v[90:91], v[78:79], off offset:-1536
	global_load_dwordx2 v[88:89], v[78:79], off offset:-1024
	global_load_dwordx2 v[82:83], v[78:79], off offset:-512
	global_load_dwordx2 v[80:81], v[78:79], off
	v_addc_co_u32_e32 v85, vcc, 0, v105, vcc
	global_load_dwordx2 v[174:175], v186, s[4:5]
	global_load_dwordx2 v[176:177], v[84:85], off
	v_add_co_u32_e32 v84, vcc, s6, v104
	v_addc_co_u32_e32 v85, vcc, 0, v105, vcc
	global_load_dwordx2 v[164:165], v[84:85], off
	v_add_co_u32_e32 v84, vcc, s76, v104
	s_nop 0
	v_addc_co_u32_e32 v85, vcc, 0, v105, vcc
	global_load_dwordx2 v[162:163], v[84:85], off
	v_add_co_u32_e32 v84, vcc, s7, v104
	s_nop 0
	v_addc_co_u32_e32 v85, vcc, 0, v105, vcc
	global_load_dwordx2 v[170:171], v[84:85], off
	v_add_co_u32_e32 v84, vcc, s36, v104
	s_nop 0
	v_addc_co_u32_e32 v85, vcc, 0, v105, vcc
	global_load_dwordx2 v[166:167], v[84:85], off
	v_add_co_u32_e32 v84, vcc, s2, v104
	v_addc_co_u32_e32 v85, vcc, 0, v105, vcc
	global_load_dwordx2 v[168:169], v[84:85], off
	v_add_co_u32_e32 v84, vcc, s91, v104
	s_nop 0
	v_addc_co_u32_e32 v85, vcc, 0, v105, vcc
	global_load_dwordx2 v[172:173], v[84:85], off
	v_add_co_u32_e32 v84, vcc, s60, v104
	s_nop 0
	v_addc_co_u32_e32 v85, vcc, 0, v105, vcc
	global_load_dwordx2 v[156:157], v[84:85], off
	v_add_co_u32_e32 v84, vcc, s68, v104
	s_nop 0
	v_addc_co_u32_e32 v85, vcc, 0, v105, vcc
	global_load_dwordx2 v[154:155], v[84:85], off
	v_add_co_u32_e32 v84, vcc, s61, v104
	v_addc_co_u32_e32 v85, vcc, 0, v105, vcc
	global_load_dwordx2 v[152:153], v[84:85], off
	v_add_co_u32_e32 v84, vcc, s24, v104
	s_nop 0
	v_addc_co_u32_e32 v85, vcc, 0, v105, vcc
	global_load_dwordx2 v[148:149], v[84:85], off
	v_add_co_u32_e32 v84, vcc, s17, v104
	s_nop 0
	v_addc_co_u32_e32 v85, vcc, 0, v105, vcc
	global_load_dwordx2 v[150:151], v[84:85], off
	v_add_co_u32_e32 v84, vcc, s93, v104
	s_nop 0
	v_addc_co_u32_e32 v85, vcc, 0, v105, vcc
	v_add_co_u32_e32 v86, vcc, s62, v104
	global_load_dwordx2 v[84:85], v[84:85], off
	s_nop 0
	v_addc_co_u32_e32 v87, vcc, 0, v105, vcc
	v_add_co_u32_e32 v92, vcc, s59, v104
	global_load_dwordx2 v[86:87], v[86:87], off
	s_nop 0
	v_addc_co_u32_e32 v93, vcc, 0, v105, vcc
	global_load_dwordx2 v[146:147], v[92:93], off
	v_add_co_u32_e32 v92, vcc, s86, v104
	v_addc_co_u32_e32 v93, vcc, 0, v105, vcc
	global_load_dwordx2 v[132:133], v[92:93], off
	v_add_co_u32_e32 v92, vcc, s69, v104
	s_nop 0
	v_addc_co_u32_e32 v93, vcc, 0, v105, vcc
	global_load_dwordx2 v[130:131], v[92:93], off
	v_add_co_u32_e32 v92, vcc, s25, v104
	s_nop 0
	v_addc_co_u32_e32 v93, vcc, 0, v105, vcc
	v_add_co_u32_e32 v94, vcc, s40, v104
	global_load_dwordx2 v[92:93], v[92:93], off
	s_nop 0
	v_addc_co_u32_e32 v95, vcc, 0, v105, vcc
	v_add_co_u32_e32 v100, vcc, s41, v104
	global_load_dwordx2 v[94:95], v[94:95], off
	s_nop 0
	v_addc_co_u32_e32 v101, vcc, 0, v105, vcc
	global_load_dwordx2 v[138:139], v[100:101], off
	v_add_co_u32_e32 v100, vcc, s48, v104
	s_nop 0
	v_addc_co_u32_e32 v101, vcc, 0, v105, vcc
	global_load_dwordx2 v[134:135], v[100:101], off
	v_add_co_u32_e32 v100, vcc, s52, v104
	v_addc_co_u32_e32 v101, vcc, 0, v105, vcc
	global_load_dwordx2 v[136:137], v[100:101], off
	v_add_co_u32_e32 v100, vcc, s53, v104
	s_nop 0
	v_addc_co_u32_e32 v101, vcc, 0, v105, vcc
	global_load_dwordx2 v[140:141], v[100:101], off
	v_add_co_u32_e32 v100, vcc, s16, v104
	s_nop 0
	v_addc_co_u32_e32 v101, vcc, 0, v105, vcc
	global_load_dwordx2 v[122:123], v[100:101], off
	v_add_co_u32_e32 v100, vcc, s54, v104
	s_nop 0
	v_addc_co_u32_e32 v101, vcc, 0, v105, vcc
	global_load_dwordx2 v[118:119], v[100:101], off
	v_add_co_u32_e32 v100, vcc, s84, v104
	v_addc_co_u32_e32 v101, vcc, 0, v105, vcc
	global_load_dwordx2 v[114:115], v[100:101], off
	v_add_co_u32_e32 v100, vcc, s30, v104
	s_nop 0
	v_addc_co_u32_e32 v101, vcc, 0, v105, vcc
	v_add_co_u32_e32 v102, vcc, s65, v104
	global_load_dwordx2 v[100:101], v[100:101], off
	s_nop 0
	v_addc_co_u32_e32 v103, vcc, 0, v105, vcc
	global_load_dwordx2 v[124:125], v[102:103], off
	v_add_co_u32_e32 v102, vcc, s33, v104
	v_addc_co_u32_e32 v103, vcc, 0, v105, vcc
	global_load_dwordx2 v[116:117], v[102:103], off
	v_add_co_u32_e32 v102, vcc, s80, v104
	s_nop 0
	v_addc_co_u32_e32 v103, vcc, 0, v105, vcc
	v_add_co_u32_e32 v110, vcc, s85, v104
	global_load_dwordx2 v[102:103], v[102:103], off
	s_nop 0
	v_addc_co_u32_e32 v111, vcc, 0, v105, vcc
	global_load_dwordx2 v[126:127], v[110:111], off
	s_waitcnt vmcnt(39)
	v_lshlrev_b32_e32 v184, 16, v108
	v_and_b32_e32 v185, 0xffff0000, v108
	v_lshlrev_b32_e32 v188, 16, v109
	v_and_b32_e32 v189, 0xffff0000, v109
	s_waitcnt vmcnt(38)
	v_lshlrev_b32_e32 v158, 16, v106
	v_and_b32_e32 v159, 0xffff0000, v106
	v_lshlrev_b32_e32 v160, 16, v107
	v_and_b32_e32 v161, 0xffff0000, v107
	s_waitcnt vmcnt(37)
	v_lshlrev_b32_e32 v142, 16, v98
	v_and_b32_e32 v143, 0xffff0000, v98
	v_lshlrev_b32_e32 v144, 16, v99
	v_and_b32_e32 v145, 0xffff0000, v99
	s_waitcnt vmcnt(36)
; __device__ __forceinline__ void norm_load(const bf16_t* xrow, f32x4 (&v)[8], int lane) {
;     ...
;     for (int j = 0; j < 8; ++j) v[j] = (f32x4){bf_lo(r[j].x), bf_hi(r[j].x), bf_lo(r[j].y), bf_hi(r[j].y)};
; template <int MODE>
; __device__ __forceinline__ void norm_apply(f32x4 (&v)[8], bf16_t* xcopy, const f32x4 (&GG)[8], const f32x4 (&SS)[8], bf16_t* obf, float* of32, int lane, const float* slabrow = nullptr, const float* gate = nullptr) {
;     ...
;         for (int jh = 0; jh < 2; ++jh) { u32x2 p[4][8];
; #pragma unroll
;             for (int jj = 0; jj < 4; ++jj) { const int j = jh * 4 + jj; const u32x2* sp = (const u32x2*)((const bf16_t*)slabrow + (size_t)j * 8 * 65536) + lane;
; #pragma unroll
;                 for (int s = 0; s < 8; ++s) p[jj][s] = sp[(size_t)s * 16384]; }
;             __builtin_amdgcn_sched_barrier(0);
; #pragma unroll
;             for (int jj = 0; jj < 4; ++jj) { const int j = jh * 4 + jj; const f32x4 gt = ((const f32x4*)gate)[lane + 64 * j];
;                 f32x4 a = {bf_lo(p[jj][0].x), bf_hi(p[jj][0].x), bf_lo(p[jj][0].y), bf_hi(p[jj][0].y)};
; #pragma unroll
;                 for (int s = 1; s < 8; ++s) a += (f32x4){bf_lo(p[jj][s].x), bf_hi(p[jj][s].x), bf_lo(p[jj][s].y), bf_hi(p[jj][s].y)};
;                 v[j] += gt * a; }
	v_lshlrev_b32_e32 v120, 16, v96
	v_and_b32_e32 v121, 0xffff0000, v96
	v_lshlrev_b32_e32 v128, 16, v97
	v_and_b32_e32 v129, 0xffff0000, v97
	s_waitcnt vmcnt(35)
	v_lshlrev_b32_e32 v106, 16, v90
	v_and_b32_e32 v107, 0xffff0000, v90
	v_lshlrev_b32_e32 v112, 16, v91
	v_and_b32_e32 v113, 0xffff0000, v91
	s_waitcnt vmcnt(34)
	v_lshlrev_b32_e32 v108, 16, v88
	v_and_b32_e32 v109, 0xffff0000, v88
	s_waitcnt vmcnt(33)
	v_lshlrev_b32_e32 v96, 16, v82
	v_and_b32_e32 v97, 0xffff0000, v82
	v_lshlrev_b32_e32 v110, 16, v89
	v_and_b32_e32 v111, 0xffff0000, v89
	v_lshlrev_b32_e32 v98, 16, v83
	v_and_b32_e32 v99, 0xffff0000, v83
	s_waitcnt vmcnt(32)
	v_lshlrev_b32_e32 v88, 16, v80
	v_and_b32_e32 v89, 0xffff0000, v80
	v_lshlrev_b32_e32 v90, 16, v81
	v_and_b32_e32 v91, 0xffff0000, v81
	global_load_dwordx4 v[190:193], v[66:67], off
	s_waitcnt vmcnt(32)
	v_lshlrev_b32_e32 v80, 16, v174
	v_and_b32_e32 v81, 0xffff0000, v174
	v_lshlrev_b32_e32 v82, 16, v175
	v_and_b32_e32 v83, 0xffff0000, v175
	s_waitcnt vmcnt(31)
	v_lshlrev_b32_e32 v174, 16, v176
	v_and_b32_e32 v175, 0xffff0000, v176
	v_lshlrev_b32_e32 v176, 16, v177
	v_and_b32_e32 v177, 0xffff0000, v177
	v_pk_add_f32 v[80:81], v[80:81], v[174:175]
	v_pk_add_f32 v[82:83], v[82:83], v[176:177]
	s_waitcnt vmcnt(30)
	v_lshlrev_b32_e32 v174, 16, v164
	v_and_b32_e32 v175, 0xffff0000, v164
	v_lshlrev_b32_e32 v164, 16, v165
	v_and_b32_e32 v165, 0xffff0000, v165
	v_pk_add_f32 v[82:83], v[82:83], v[164:165]
	v_pk_add_f32 v[80:81], v[80:81], v[174:175]
	s_waitcnt vmcnt(29)
	v_lshlrev_b32_e32 v164, 16, v162
	v_and_b32_e32 v165, 0xffff0000, v162
	v_lshlrev_b32_e32 v162, 16, v163
	v_and_b32_e32 v163, 0xffff0000, v163
	v_pk_add_f32 v[80:81], v[80:81], v[164:165]
	v_pk_add_f32 v[82:83], v[82:83], v[162:163]
	s_waitcnt vmcnt(28)
	v_lshlrev_b32_e32 v162, 16, v170
	v_and_b32_e32 v163, 0xffff0000, v170
	v_lshlrev_b32_e32 v164, 16, v171
	v_and_b32_e32 v165, 0xffff0000, v171
	v_pk_add_f32 v[82:83], v[82:83], v[164:165]
	v_pk_add_f32 v[80:81], v[80:81], v[162:163]
	s_waitcnt vmcnt(27)
	v_lshlrev_b32_e32 v162, 16, v166
	v_and_b32_e32 v163, 0xffff0000, v166
	v_lshlrev_b32_e32 v164, 16, v167
	v_and_b32_e32 v165, 0xffff0000, v167
	v_pk_add_f32 v[80:81], v[80:81], v[162:163]
	v_pk_add_f32 v[82:83], v[82:83], v[164:165]
	s_waitcnt vmcnt(26)
	v_lshlrev_b32_e32 v162, 16, v168
	v_and_b32_e32 v163, 0xffff0000, v168
	v_lshlrev_b32_e32 v164, 16, v169
	v_and_b32_e32 v165, 0xffff0000, v169
	s_waitcnt vmcnt(24)
	v_lshlrev_b32_e32 v166, 16, v156
	v_and_b32_e32 v167, 0xffff0000, v156
	v_lshlrev_b32_e32 v156, 16, v157
	v_and_b32_e32 v157, 0xffff0000, v157
	s_waitcnt vmcnt(23)
	v_lshlrev_b32_e32 v168, 16, v154
	v_and_b32_e32 v169, 0xffff0000, v154
	v_lshlrev_b32_e32 v154, 16, v155
	v_and_b32_e32 v155, 0xffff0000, v155
	v_pk_add_f32 v[166:167], v[166:167], v[168:169]
	v_pk_add_f32 v[154:155], v[156:157], v[154:155]
	s_waitcnt vmcnt(22)
	v_lshlrev_b32_e32 v156, 16, v152
	v_and_b32_e32 v157, 0xffff0000, v152
	v_lshlrev_b32_e32 v152, 16, v153
	v_and_b32_e32 v153, 0xffff0000, v153
	v_pk_add_f32 v[152:153], v[154:155], v[152:153]
	v_pk_add_f32 v[154:155], v[166:167], v[156:157]
	s_waitcnt vmcnt(21)
	v_lshlrev_b32_e32 v156, 16, v148
	v_and_b32_e32 v157, 0xffff0000, v148
	v_lshlrev_b32_e32 v148, 16, v149
	v_and_b32_e32 v149, 0xffff0000, v149
	v_pk_add_f32 v[154:155], v[154:155], v[156:157]
	v_pk_add_f32 v[148:149], v[152:153], v[148:149]
	s_waitcnt vmcnt(20)
	v_lshlrev_b32_e32 v152, 16, v150
	v_and_b32_e32 v153, 0xffff0000, v150
	v_lshlrev_b32_e32 v150, 16, v151
	v_and_b32_e32 v151, 0xffff0000, v151
	v_pk_add_f32 v[148:149], v[148:149], v[150:151]
	v_pk_add_f32 v[150:151], v[154:155], v[152:153]
	s_waitcnt vmcnt(19)
	v_lshlrev_b32_e32 v152, 16, v84
	v_and_b32_e32 v153, 0xffff0000, v84
	v_lshlrev_b32_e32 v84, 16, v85
	v_and_b32_e32 v85, 0xffff0000, v85
	v_pk_add_f32 v[150:151], v[150:151], v[152:153]
	v_pk_add_f32 v[84:85], v[148:149], v[84:85]
	s_waitcnt vmcnt(18)
	v_lshlrev_b32_e32 v148, 16, v86
	v_and_b32_e32 v149, 0xffff0000, v86
	v_lshlrev_b32_e32 v86, 16, v87
	v_and_b32_e32 v87, 0xffff0000, v87
	v_pk_add_f32 v[84:85], v[84:85], v[86:87]
	v_pk_add_f32 v[86:87], v[150:151], v[148:149]
	s_waitcnt vmcnt(16)
	v_lshlrev_b32_e32 v150, 16, v132
	v_and_b32_e32 v151, 0xffff0000, v132
	v_lshlrev_b32_e32 v132, 16, v133
	v_and_b32_e32 v133, 0xffff0000, v133
	s_waitcnt vmcnt(15)
	v_lshlrev_b32_e32 v152, 16, v130
	v_and_b32_e32 v153, 0xffff0000, v130
	v_lshlrev_b32_e32 v130, 16, v131
	v_and_b32_e32 v131, 0xffff0000, v131
	v_pk_add_f32 v[150:151], v[150:151], v[152:153]
	v_pk_add_f32 v[130:131], v[132:133], v[130:131]
	s_waitcnt vmcnt(14)
	v_lshlrev_b32_e32 v132, 16, v92
	v_and_b32_e32 v133, 0xffff0000, v92
	v_lshlrev_b32_e32 v92, 16, v93
	v_and_b32_e32 v93, 0xffff0000, v93
	v_pk_add_f32 v[92:93], v[130:131], v[92:93]
	v_pk_add_f32 v[130:131], v[150:151], v[132:133]
	s_waitcnt vmcnt(13)
	v_lshlrev_b32_e32 v132, 16, v94
	v_and_b32_e32 v133, 0xffff0000, v94
	v_lshlrev_b32_e32 v94, 16, v95
	v_and_b32_e32 v95, 0xffff0000, v95
	v_pk_add_f32 v[130:131], v[130:131], v[132:133]
	v_pk_add_f32 v[92:93], v[92:93], v[94:95]
	s_waitcnt vmcnt(12)
	v_lshlrev_b32_e32 v94, 16, v138
	v_and_b32_e32 v95, 0xffff0000, v138
	v_lshlrev_b32_e32 v132, 16, v139
	v_and_b32_e32 v133, 0xffff0000, v139
	v_pk_add_f32 v[92:93], v[92:93], v[132:133]
	v_pk_add_f32 v[94:95], v[130:131], v[94:95]
	s_waitcnt vmcnt(11)
	v_lshlrev_b32_e32 v130, 16, v134
	v_and_b32_e32 v131, 0xffff0000, v134
	v_lshlrev_b32_e32 v132, 16, v135
	v_and_b32_e32 v133, 0xffff0000, v135
	v_pk_add_f32 v[80:81], v[80:81], v[162:163]
	v_lshlrev_b32_e32 v162, 16, v172
	v_and_b32_e32 v163, 0xffff0000, v172
	v_pk_add_f32 v[94:95], v[94:95], v[130:131]
	v_pk_add_f32 v[92:93], v[92:93], v[132:133]
	s_waitcnt vmcnt(10)
; template <int MODE>
; __device__ __forceinline__ void norm_apply(f32x4 (&v)[8], bf16_t* xcopy, const f32x4 (&GG)[8], const f32x4 (&SS)[8], bf16_t* obf, float* of32, int lane, const float* slabrow = nullptr, const float* gate = nullptr) {
;     ...
;         for (int jh = 0; jh < 2; ++jh) { u32x2 p[4][8];
; #pragma unroll
;             for (int jj = 0; jj < 4; ++jj) { const int j = jh * 4 + jj; const u32x2* sp = (const u32x2*)((const bf16_t*)slabrow + (size_t)j * 8 * 65536) + lane;
; #pragma unroll
;                 for (int s = 0; s < 8; ++s) p[jj][s] = sp[(size_t)s * 16384]; }
;             __builtin_amdgcn_sched_barrier(0);
; #pragma unroll
;             for (int jj = 0; jj < 4; ++jj) { const int j = jh * 4 + jj; const f32x4 gt = ((const f32x4*)gate)[lane + 64 * j];
;                 f32x4 a = {bf_lo(p[jj][0].x), bf_hi(p[jj][0].x), bf_lo(p[jj][0].y), bf_hi(p[jj][0].y)};
; #pragma unroll
;                 for (int s = 1; s < 8; ++s) a += (f32x4){bf_lo(p[jj][s].x), bf_hi(p[jj][s].x), bf_lo(p[jj][s].y), bf_hi(p[jj][s].y)};
;                 v[j] += gt * a; }
	v_lshlrev_b32_e32 v130, 16, v136
	v_and_b32_e32 v131, 0xffff0000, v136
	v_lshlrev_b32_e32 v132, 16, v137
	v_and_b32_e32 v133, 0xffff0000, v137
	v_pk_add_f32 v[82:83], v[82:83], v[164:165]
	v_lshlrev_b32_e32 v164, 16, v173
	v_and_b32_e32 v165, 0xffff0000, v173
	v_pk_add_f32 v[162:163], v[80:81], v[162:163]
	v_lshlrev_b32_e32 v148, 16, v146
	v_and_b32_e32 v149, 0xffff0000, v146
	v_lshlrev_b32_e32 v146, 16, v147
	v_and_b32_e32 v147, 0xffff0000, v147
	v_pk_add_f32 v[92:93], v[92:93], v[132:133]
	v_pk_add_f32 v[94:95], v[94:95], v[130:131]
	s_waitcnt vmcnt(9)
	v_lshlrev_b32_e32 v130, 16, v140
	v_and_b32_e32 v131, 0xffff0000, v140
	v_lshlrev_b32_e32 v132, 16, v141
	v_and_b32_e32 v133, 0xffff0000, v141
	v_pk_add_f32 v[80:81], v[82:83], v[164:165]
	v_pk_add_f32 v[86:87], v[86:87], v[148:149]
	v_pk_add_f32 v[84:85], v[84:85], v[146:147]
	global_load_dwordx4 v[146:149], v[66:67], off offset:2048
	s_waitcnt vmcnt(1)
	v_pk_fma_f32 v[82:83], v[162:163], v[190:191], v[184:185]
	global_load_dwordx4 v[162:165], v[66:67], off offset:1024
	v_pk_add_f32 v[94:95], v[94:95], v[130:131]
	v_pk_add_f32 v[92:93], v[92:93], v[132:133]
	global_load_dwordx4 v[130:133], v[66:67], off offset:3072
	v_lshlrev_b32_e32 v134, 16, v122
	v_and_b32_e32 v135, 0xffff0000, v122
	v_lshlrev_b32_e32 v122, 16, v123
	v_and_b32_e32 v123, 0xffff0000, v123
	v_lshlrev_b32_e32 v136, 16, v118
	v_and_b32_e32 v137, 0xffff0000, v118
	v_lshlrev_b32_e32 v118, 16, v119
	v_and_b32_e32 v119, 0xffff0000, v119
	v_pk_add_f32 v[134:135], v[134:135], v[136:137]
	v_pk_add_f32 v[118:119], v[122:123], v[118:119]
	v_lshlrev_b32_e32 v122, 16, v114
	v_and_b32_e32 v123, 0xffff0000, v114
	v_lshlrev_b32_e32 v114, 16, v115
	v_and_b32_e32 v115, 0xffff0000, v115
	v_pk_add_f32 v[114:115], v[118:119], v[114:115]
	v_pk_add_f32 v[118:119], v[134:135], v[122:123]
	v_lshlrev_b32_e32 v122, 16, v100
	v_and_b32_e32 v123, 0xffff0000, v100
	v_lshlrev_b32_e32 v100, 16, v101
	v_and_b32_e32 v101, 0xffff0000, v101
	v_pk_add_f32 v[118:119], v[118:119], v[122:123]
	v_pk_add_f32 v[100:101], v[114:115], v[100:101]
	v_lshlrev_b32_e32 v114, 16, v124
	v_and_b32_e32 v115, 0xffff0000, v124
	v_lshlrev_b32_e32 v122, 16, v125
	v_and_b32_e32 v123, 0xffff0000, v125
	v_pk_add_f32 v[100:101], v[100:101], v[122:123]
	v_pk_add_f32 v[114:115], v[118:119], v[114:115]
	v_lshlrev_b32_e32 v118, 16, v116
	v_and_b32_e32 v119, 0xffff0000, v116
	v_lshlrev_b32_e32 v116, 16, v117
	v_and_b32_e32 v117, 0xffff0000, v117
	v_pk_add_f32 v[114:115], v[114:115], v[118:119]
	v_pk_add_f32 v[100:101], v[100:101], v[116:117]
	v_lshlrev_b32_e32 v116, 16, v102
	v_and_b32_e32 v117, 0xffff0000, v102
	v_lshlrev_b32_e32 v102, 16, v103
	v_and_b32_e32 v103, 0xffff0000, v103
	v_pk_add_f32 v[100:101], v[100:101], v[102:103]
	v_pk_add_f32 v[102:103], v[114:115], v[116:117]
	v_lshlrev_b32_e32 v114, 16, v126
	v_and_b32_e32 v115, 0xffff0000, v126
	v_lshlrev_b32_e32 v116, 16, v127
	v_and_b32_e32 v117, 0xffff0000, v127
	v_pk_add_f32 v[102:103], v[102:103], v[114:115]
	v_pk_add_f32 v[100:101], v[100:101], v[116:117]
	v_pk_fma_f32 v[80:81], v[80:81], v[192:193], v[188:189]
	s_waitcnt vmcnt(2)
	v_pk_fma_f32 v[92:93], v[92:93], v[148:149], v[144:145]
	v_pk_fma_f32 v[94:95], v[94:95], v[146:147], v[142:143]
	s_waitcnt vmcnt(1)
	v_pk_fma_f32 v[84:85], v[84:85], v[164:165], v[160:161]
	v_pk_fma_f32 v[86:87], v[86:87], v[162:163], v[158:159]
	s_waitcnt vmcnt(0)
	v_pk_fma_f32 v[100:101], v[132:133], v[100:101], v[128:129]
	v_pk_fma_f32 v[102:103], v[130:131], v[102:103], v[120:121]
	v_add_co_u32_e32 v114, vcc, s78, v104
	s_nop 1
	v_addc_co_u32_e32 v115, vcc, 0, v105, vcc
	v_add_co_u32_e32 v116, vcc, s94, v104
	s_nop 1
	v_addc_co_u32_e32 v117, vcc, 0, v105, vcc
	v_add_co_u32_e32 v118, vcc, s73, v104
	s_nop 1
	v_addc_co_u32_e32 v119, vcc, 0, v105, vcc
	v_add_co_u32_e32 v120, vcc, s83, v104
	s_nop 1
	v_addc_co_u32_e32 v121, vcc, 0, v105, vcc
	global_load_dwordx2 v[166:167], v[114:115], off
	global_load_dwordx2 v[168:169], v[116:117], off
	global_load_dwordx2 v[170:171], v[118:119], off
	global_load_dwordx2 v[172:173], v[120:121], off
	v_add_co_u32_e32 v114, vcc, s31, v104
	s_nop 1
	v_addc_co_u32_e32 v115, vcc, 0, v105, vcc
	v_add_co_u32_e32 v116, vcc, s43, v104
	s_nop 1
	v_addc_co_u32_e32 v117, vcc, 0, v105, vcc
	v_add_co_u32_e32 v118, vcc, s90, v104
	s_nop 1
	v_addc_co_u32_e32 v119, vcc, 0, v105, vcc
	v_add_co_u32_e32 v120, vcc, s34, v104
	s_nop 1
	v_addc_co_u32_e32 v121, vcc, 0, v105, vcc
	global_load_dwordx2 v[174:175], v[114:115], off
	global_load_dwordx2 v[176:177], v[116:117], off
	global_load_dwordx2 v[184:185], v[118:119], off
	global_load_dwordx2 v[188:189], v[120:121], off
	v_add_co_u32_e32 v114, vcc, s46, v104
	s_nop 1
	v_addc_co_u32_e32 v115, vcc, 0, v105, vcc
	v_add_co_u32_e32 v116, vcc, s97, v104
	s_nop 1
	v_addc_co_u32_e32 v117, vcc, 0, v105, vcc
	v_add_co_u32_e32 v118, vcc, s37, v104
	s_nop 1
	v_addc_co_u32_e32 v119, vcc, 0, v105, vcc
	v_add_co_u32_e32 v120, vcc, s55, v104
	s_nop 1
	v_addc_co_u32_e32 v121, vcc, 0, v105, vcc
	global_load_dwordx2 v[160:161], v[114:115], off
	global_load_dwordx2 v[158:159], v[116:117], off
	global_load_dwordx2 v[156:157], v[118:119], off
	global_load_dwordx2 v[152:153], v[120:121], off
	v_add_co_u32_e32 v114, vcc, s95, v104
	s_nop 1
	v_addc_co_u32_e32 v115, vcc, 0, v105, vcc
	v_add_co_u32_e32 v116, vcc, s79, v104
	s_nop 1
	v_addc_co_u32_e32 v117, vcc, 0, v105, vcc
	v_add_co_u32_e32 v118, vcc, s81, v104
	s_nop 1
	v_addc_co_u32_e32 v119, vcc, 0, v105, vcc
	v_add_co_u32_e32 v120, vcc, s75, v104
	s_nop 1
	v_addc_co_u32_e32 v121, vcc, 0, v105, vcc
	global_load_dwordx2 v[154:155], v[114:115], off
	global_load_dwordx2 v[150:151], v[116:117], off
; template <int MODE>
; __device__ __forceinline__ void norm_apply(f32x4 (&v)[8], bf16_t* xcopy, const f32x4 (&GG)[8], const f32x4 (&SS)[8], bf16_t* obf, float* of32, int lane, const float* slabrow = nullptr, const float* gate = nullptr) {
;     ...
;         for (int jh = 0; jh < 2; ++jh) { u32x2 p[4][8];
; #pragma unroll
;             for (int jj = 0; jj < 4; ++jj) { const int j = jh * 4 + jj; const u32x2* sp = (const u32x2*)((const bf16_t*)slabrow + (size_t)j * 8 * 65536) + lane;
; #pragma unroll
;                 for (int s = 0; s < 8; ++s) p[jj][s] = sp[(size_t)s * 16384]; }
;             __builtin_amdgcn_sched_barrier(0);
; #pragma unroll
;             for (int jj = 0; jj < 4; ++jj) { const int j = jh * 4 + jj; const f32x4 gt = ((const f32x4*)gate)[lane + 64 * j];
;                 f32x4 a = {bf_lo(p[jj][0].x), bf_hi(p[jj][0].x), bf_lo(p[jj][0].y), bf_hi(p[jj][0].y)};
; #pragma unroll
;                 for (int s = 1; s < 8; ++s) a += (f32x4){bf_lo(p[jj][s].x), bf_hi(p[jj][s].x), bf_lo(p[jj][s].y), bf_hi(p[jj][s].y)};
;                 v[j] += gt * a; }
	global_load_dwordx2 v[148:149], v[118:119], off
	global_load_dwordx2 v[146:147], v[120:121], off
	v_add_co_u32_e32 v114, vcc, s35, v104
	s_nop 1
	v_addc_co_u32_e32 v115, vcc, 0, v105, vcc
	v_add_co_u32_e32 v116, vcc, s87, v104
	s_nop 1
	v_addc_co_u32_e32 v117, vcc, 0, v105, vcc
	v_add_co_u32_e32 v118, vcc, s96, v104
	s_nop 1
	v_addc_co_u32_e32 v119, vcc, 0, v105, vcc
	v_add_co_u32_e32 v120, vcc, s38, v104
	s_nop 1
	v_addc_co_u32_e32 v121, vcc, 0, v105, vcc
	global_load_dwordx2 v[144:145], v[114:115], off
	global_load_dwordx2 v[142:143], v[116:117], off
	global_load_dwordx2 v[136:137], v[118:119], off
	global_load_dwordx2 v[132:133], v[120:121], off
	v_add_co_u32_e32 v114, vcc, s74, v104
	s_nop 1
	v_addc_co_u32_e32 v115, vcc, 0, v105, vcc
	v_add_co_u32_e32 v116, vcc, s71, v104
	s_nop 1
	v_addc_co_u32_e32 v117, vcc, 0, v105, vcc
	v_add_co_u32_e32 v118, vcc, s57, v104
	s_nop 1
	v_addc_co_u32_e32 v119, vcc, 0, v105, vcc
	v_add_co_u32_e32 v120, vcc, s44, v104
	s_nop 1
	v_addc_co_u32_e32 v121, vcc, 0, v105, vcc
	global_load_dwordx2 v[140:141], v[114:115], off
	global_load_dwordx2 v[138:139], v[116:117], off
	global_load_dwordx2 v[134:135], v[118:119], off
	global_load_dwordx2 v[130:131], v[120:121], off
	v_add_co_u32_e32 v114, vcc, s45, v104
	s_nop 1
	v_addc_co_u32_e32 v115, vcc, 0, v105, vcc
	v_add_co_u32_e32 v116, vcc, s50, v104
	s_nop 1
	v_addc_co_u32_e32 v117, vcc, 0, v105, vcc
	v_add_co_u32_e32 v118, vcc, s47, v104
	s_nop 1
	v_addc_co_u32_e32 v119, vcc, 0, v105, vcc
	v_add_co_u32_e32 v120, vcc, s51, v104
	s_nop 1
	v_addc_co_u32_e32 v121, vcc, 0, v105, vcc
	global_load_dwordx2 v[128:129], v[114:115], off
	global_load_dwordx2 v[126:127], v[116:117], off
	global_load_dwordx2 v[122:123], v[118:119], off
	s_nop 0
	global_load_dwordx2 v[120:121], v[120:121], off
	v_add_co_u32_e32 v114, vcc, s39, v104
	s_nop 1
	v_addc_co_u32_e32 v115, vcc, 0, v105, vcc
	v_add_co_u32_e32 v116, vcc, s67, v104
	s_nop 1
	v_addc_co_u32_e32 v117, vcc, 0, v105, vcc
	v_add_co_u32_e32 v162, vcc, s72, v104
	s_nop 1
	v_addc_co_u32_e32 v163, vcc, 0, v105, vcc
	v_add_co_u32_e32 v104, vcc, s66, v104
	s_nop 1
	v_addc_co_u32_e32 v105, vcc, 0, v105, vcc
	global_load_dwordx2 v[124:125], v[114:115], off
	global_load_dwordx2 v[118:119], v[116:117], off
	s_nop 0
	global_load_dwordx2 v[116:117], v[162:163], off
	global_load_dwordx2 v[114:115], v[104:105], off
	s_nop 0
	global_load_dwordx4 v[162:165], v[68:69], off
	s_waitcnt vmcnt(32)
	v_lshlrev_b32_e32 v104, 16, v166
	v_and_b32_e32 v105, 0xffff0000, v166
	v_lshlrev_b32_e32 v166, 16, v167
	v_and_b32_e32 v167, 0xffff0000, v167
	s_waitcnt vmcnt(31)
	v_lshlrev_b32_e32 v190, 16, v168
	v_and_b32_e32 v191, 0xffff0000, v168
	v_lshlrev_b32_e32 v168, 16, v169
	v_and_b32_e32 v169, 0xffff0000, v169
	v_pk_add_f32 v[104:105], v[104:105], v[190:191]
	v_pk_add_f32 v[166:167], v[166:167], v[168:169]
	s_waitcnt vmcnt(30)
	v_lshlrev_b32_e32 v168, 16, v170
	v_and_b32_e32 v169, 0xffff0000, v170
	v_lshlrev_b32_e32 v170, 16, v171
	v_and_b32_e32 v171, 0xffff0000, v171
	v_pk_add_f32 v[166:167], v[166:167], v[170:171]
	v_pk_add_f32 v[104:105], v[104:105], v[168:169]
	s_waitcnt vmcnt(29)
	v_lshlrev_b32_e32 v168, 16, v172
	v_and_b32_e32 v169, 0xffff0000, v172
	v_lshlrev_b32_e32 v170, 16, v173
	v_and_b32_e32 v171, 0xffff0000, v173
	v_pk_add_f32 v[104:105], v[104:105], v[168:169]
	v_pk_add_f32 v[166:167], v[166:167], v[170:171]
	s_waitcnt vmcnt(28)
	v_lshlrev_b32_e32 v168, 16, v174
	v_and_b32_e32 v169, 0xffff0000, v174
	v_lshlrev_b32_e32 v170, 16, v175
	v_and_b32_e32 v171, 0xffff0000, v175
	v_pk_add_f32 v[166:167], v[166:167], v[170:171]
	v_pk_add_f32 v[104:105], v[104:105], v[168:169]
	s_waitcnt vmcnt(27)
	v_lshlrev_b32_e32 v168, 16, v176
	v_and_b32_e32 v169, 0xffff0000, v176
	v_lshlrev_b32_e32 v170, 16, v177
	v_and_b32_e32 v171, 0xffff0000, v177
	v_pk_add_f32 v[104:105], v[104:105], v[168:169]
	v_pk_add_f32 v[166:167], v[166:167], v[170:171]
	s_waitcnt vmcnt(26)
	v_lshlrev_b32_e32 v168, 16, v184
	v_and_b32_e32 v169, 0xffff0000, v184
	v_lshlrev_b32_e32 v170, 16, v185
	v_and_b32_e32 v171, 0xffff0000, v185
	v_pk_add_f32 v[166:167], v[166:167], v[170:171]
	v_pk_add_f32 v[104:105], v[104:105], v[168:169]
	s_waitcnt vmcnt(25)
	v_lshlrev_b32_e32 v168, 16, v188
	v_and_b32_e32 v169, 0xffff0000, v188
	v_lshlrev_b32_e32 v170, 16, v189
	v_and_b32_e32 v171, 0xffff0000, v189
	v_pk_add_f32 v[168:169], v[104:105], v[168:169]
	v_pk_add_f32 v[104:105], v[166:167], v[170:171]
	s_waitcnt vmcnt(23)
	v_lshlrev_b32_e32 v166, 16, v158
	v_and_b32_e32 v167, 0xffff0000, v158
	v_lshlrev_b32_e32 v158, 16, v159
	v_and_b32_e32 v159, 0xffff0000, v159
	s_waitcnt vmcnt(0)
	v_pk_fma_f32 v[104:105], v[104:105], v[164:165], v[112:113]
	v_pk_fma_f32 v[106:107], v[168:169], v[162:163], v[106:107]
	global_load_dwordx4 v[162:165], v[70:71], off
	v_lshlrev_b32_e32 v112, 16, v160
	v_and_b32_e32 v113, 0xffff0000, v160
	v_lshlrev_b32_e32 v160, 16, v161
	v_and_b32_e32 v161, 0xffff0000, v161
	v_pk_add_f32 v[158:159], v[160:161], v[158:159]
	v_lshlrev_b32_e32 v160, 16, v156
	v_and_b32_e32 v161, 0xffff0000, v156
	v_lshlrev_b32_e32 v156, 16, v157
	v_and_b32_e32 v157, 0xffff0000, v157
	v_pk_add_f32 v[156:157], v[158:159], v[156:157]
	v_lshlrev_b32_e32 v158, 16, v152
	v_and_b32_e32 v159, 0xffff0000, v152
	v_lshlrev_b32_e32 v152, 16, v153
	v_and_b32_e32 v153, 0xffff0000, v153
	v_pk_add_f32 v[152:153], v[156:157], v[152:153]
	v_lshlrev_b32_e32 v156, 16, v154
	v_and_b32_e32 v157, 0xffff0000, v154
	v_lshlrev_b32_e32 v154, 16, v155
	v_and_b32_e32 v155, 0xffff0000, v155
	v_pk_add_f32 v[152:153], v[152:153], v[154:155]
	v_lshlrev_b32_e32 v154, 16, v150
	v_and_b32_e32 v155, 0xffff0000, v150
	v_lshlrev_b32_e32 v150, 16, v151
	v_and_b32_e32 v151, 0xffff0000, v151
	v_pk_add_f32 v[150:151], v[152:153], v[150:151]
	v_lshlrev_b32_e32 v152, 16, v148
	v_and_b32_e32 v153, 0xffff0000, v148
	v_lshlrev_b32_e32 v148, 16, v149
	v_and_b32_e32 v149, 0xffff0000, v149
	v_pk_add_f32 v[148:149], v[150:151], v[148:149]
	v_lshlrev_b32_e32 v150, 16, v146
	v_and_b32_e32 v151, 0xffff0000, v146
	v_lshlrev_b32_e32 v146, 16, v147
	v_and_b32_e32 v147, 0xffff0000, v147
	v_pk_add_f32 v[146:147], v[148:149], v[146:147]
	v_pk_add_f32 v[112:113], v[112:113], v[166:167]
	s_waitcnt vmcnt(0)
; template <int MODE>
; __device__ __forceinline__ void norm_apply(f32x4 (&v)[8], bf16_t* xcopy, const f32x4 (&GG)[8], const f32x4 (&SS)[8], bf16_t* obf, float* of32, int lane, const float* slabrow = nullptr, const float* gate = nullptr) {
;     ...
;             for (int jj = 0; jj < 4; ++jj) { const int j = jh * 4 + jj; const f32x4 gt = ((const f32x4*)gate)[lane + 64 * j];
;                 f32x4 a = {bf_lo(p[jj][0].x), bf_hi(p[jj][0].x), bf_lo(p[jj][0].y), bf_hi(p[jj][0].y)};
; #pragma unroll
;                 for (int s = 1; s < 8; ++s) a += (f32x4){bf_lo(p[jj][s].x), bf_hi(p[jj][s].x), bf_lo(p[jj][s].y), bf_hi(p[jj][s].y)};
;                 v[j] += gt * a; }
	v_pk_fma_f32 v[110:111], v[146:147], v[164:165], v[110:111]
	global_load_dwordx4 v[146:149], v[72:73], off
	v_pk_add_f32 v[112:113], v[112:113], v[160:161]
	s_nop 0
	v_pk_add_f32 v[112:113], v[112:113], v[158:159]
	s_nop 0
	v_pk_add_f32 v[112:113], v[112:113], v[156:157]
	s_nop 0
	v_pk_add_f32 v[112:113], v[112:113], v[154:155]
	s_nop 0
	v_pk_add_f32 v[112:113], v[112:113], v[152:153]
	s_nop 0
	v_pk_add_f32 v[112:113], v[112:113], v[150:151]
	v_lshlrev_b32_e32 v150, 16, v142
	v_pk_fma_f32 v[108:109], v[112:113], v[162:163], v[108:109]
	v_lshlrev_b32_e32 v112, 16, v144
	v_and_b32_e32 v113, 0xffff0000, v144
	v_lshlrev_b32_e32 v144, 16, v145
	v_and_b32_e32 v145, 0xffff0000, v145
	v_and_b32_e32 v151, 0xffff0000, v142
	v_lshlrev_b32_e32 v142, 16, v143
	v_and_b32_e32 v143, 0xffff0000, v143
	v_pk_add_f32 v[112:113], v[112:113], v[150:151]
	v_pk_add_f32 v[142:143], v[144:145], v[142:143]
	v_lshlrev_b32_e32 v144, 16, v136
	v_and_b32_e32 v145, 0xffff0000, v136
	v_lshlrev_b32_e32 v136, 16, v137
	v_and_b32_e32 v137, 0xffff0000, v137
	v_pk_add_f32 v[136:137], v[142:143], v[136:137]
	v_pk_add_f32 v[112:113], v[112:113], v[144:145]
	v_lshlrev_b32_e32 v142, 16, v132
	v_and_b32_e32 v143, 0xffff0000, v132
	v_lshlrev_b32_e32 v132, 16, v133
	v_and_b32_e32 v133, 0xffff0000, v133
	v_pk_add_f32 v[112:113], v[112:113], v[142:143]
	v_pk_add_f32 v[132:133], v[136:137], v[132:133]
	v_lshlrev_b32_e32 v136, 16, v140
	v_and_b32_e32 v137, 0xffff0000, v140
	v_lshlrev_b32_e32 v140, 16, v141
	v_and_b32_e32 v141, 0xffff0000, v141
	v_pk_add_f32 v[132:133], v[132:133], v[140:141]
	v_pk_add_f32 v[112:113], v[112:113], v[136:137]
	v_lshlrev_b32_e32 v136, 16, v138
	v_and_b32_e32 v137, 0xffff0000, v138
	v_lshlrev_b32_e32 v138, 16, v139
	v_and_b32_e32 v139, 0xffff0000, v139
	v_pk_add_f32 v[112:113], v[112:113], v[136:137]
	v_pk_add_f32 v[132:133], v[132:133], v[138:139]
	v_lshlrev_b32_e32 v136, 16, v134
	v_and_b32_e32 v137, 0xffff0000, v134
	v_lshlrev_b32_e32 v134, 16, v135
	v_and_b32_e32 v135, 0xffff0000, v135
	v_pk_add_f32 v[132:133], v[132:133], v[134:135]
	v_lshlrev_b32_e32 v134, 16, v130
	v_and_b32_e32 v135, 0xffff0000, v130
	v_lshlrev_b32_e32 v130, 16, v131
	v_and_b32_e32 v131, 0xffff0000, v131
	v_pk_add_f32 v[130:131], v[132:133], v[130:131]
	v_pk_add_f32 v[112:113], v[112:113], v[136:137]
	s_waitcnt vmcnt(0)
	v_pk_fma_f32 v[98:99], v[130:131], v[148:149], v[98:99]
	global_load_dwordx4 v[130:133], v[74:75], off
	v_pk_add_f32 v[112:113], v[112:113], v[134:135]
	v_lshlrev_b32_e32 v134, 16, v126
	v_pk_fma_f32 v[96:97], v[112:113], v[146:147], v[96:97]
	v_lshlrev_b32_e32 v112, 16, v128
	v_and_b32_e32 v113, 0xffff0000, v128
	v_lshlrev_b32_e32 v128, 16, v129
	v_and_b32_e32 v129, 0xffff0000, v129
	v_and_b32_e32 v135, 0xffff0000, v126
	v_lshlrev_b32_e32 v126, 16, v127
	v_and_b32_e32 v127, 0xffff0000, v127
	v_pk_add_f32 v[112:113], v[112:113], v[134:135]
	v_pk_add_f32 v[126:127], v[128:129], v[126:127]
	v_lshlrev_b32_e32 v128, 16, v122
	v_and_b32_e32 v129, 0xffff0000, v122
	v_lshlrev_b32_e32 v122, 16, v123
	v_and_b32_e32 v123, 0xffff0000, v123
	v_pk_add_f32 v[122:123], v[126:127], v[122:123]
	v_pk_add_f32 v[112:113], v[112:113], v[128:129]
	v_lshlrev_b32_e32 v126, 16, v120
	v_and_b32_e32 v127, 0xffff0000, v120
	v_lshlrev_b32_e32 v120, 16, v121
	v_and_b32_e32 v121, 0xffff0000, v121
	v_pk_add_f32 v[112:113], v[112:113], v[126:127]
	v_pk_add_f32 v[120:121], v[122:123], v[120:121]
	v_lshlrev_b32_e32 v122, 16, v124
	v_and_b32_e32 v123, 0xffff0000, v124
	v_lshlrev_b32_e32 v124, 16, v125
	v_and_b32_e32 v125, 0xffff0000, v125
	v_pk_add_f32 v[120:121], v[120:121], v[124:125]
	v_pk_add_f32 v[112:113], v[112:113], v[122:123]
	v_lshlrev_b32_e32 v122, 16, v118
	v_and_b32_e32 v123, 0xffff0000, v118
	v_lshlrev_b32_e32 v118, 16, v119
	v_and_b32_e32 v119, 0xffff0000, v119
	v_pk_add_f32 v[112:113], v[112:113], v[122:123]
	v_pk_add_f32 v[118:119], v[120:121], v[118:119]
	v_lshlrev_b32_e32 v120, 16, v116
	v_and_b32_e32 v121, 0xffff0000, v116
	v_lshlrev_b32_e32 v116, 16, v117
	v_and_b32_e32 v117, 0xffff0000, v117
	v_pk_add_f32 v[116:117], v[118:119], v[116:117]
	v_pk_add_f32 v[112:113], v[112:113], v[120:121]
	v_lshlrev_b32_e32 v118, 16, v114
	v_and_b32_e32 v119, 0xffff0000, v114
	v_lshlrev_b32_e32 v114, 16, v115
	v_and_b32_e32 v115, 0xffff0000, v115
	v_pk_add_f32 v[112:113], v[112:113], v[118:119]
	v_pk_add_f32 v[114:115], v[116:117], v[114:115]
	s_waitcnt vmcnt(0)
; __device__ __forceinline__ unsigned pk2(float lo, float hi) { return f2bf(lo) | (f2bf(hi) << 16); }
; __device__ __forceinline__ float wave_sum(float v) {
; #pragma unroll
;     for (int o = 1; o < 64; o <<= 1) v += __shfl_xor(v, o);
;     return v;
; template <int MODE>
; __device__ __forceinline__ void norm_apply(f32x4 (&v)[8], bf16_t* xcopy, const f32x4 (&GG)[8], const f32x4 (&SS)[8], bf16_t* obf, float* of32, int lane, const float* slabrow = nullptr, const float* gate = nullptr) {
;     ...
; #pragma unroll
;     for (int j = 0; j < 8; ++j) ss += (v[j].x * v[j].x + v[j].y * v[j].y) + (v[j].z * v[j].z + v[j].w * v[j].w);
;     const float rstd = rsqrtf(wave_sum(ss) * (1.f / D) + 1e-6f);
;     if (xcopy) {
; #pragma unroll
;         for (int j = 0; j < 8; ++j) { u32x2 w; w.x = pk2(v[j].x, v[j].y); w.y = pk2(v[j].z, v[j].w); ((u32x2*)xcopy)[lane + 64 * j] = w; } }
	v_pk_fma_f32 v[88:89], v[130:131], v[112:113], v[88:89]
	v_pk_fma_f32 v[90:91], v[132:133], v[114:115], v[90:91]
	v_mov_b32_e32 v114, v83
	v_mov_b32_e32 v115, v87
	v_mov_b32_e32 v112, v82
	v_mov_b32_e32 v113, v86
	v_pk_mul_f32 v[114:115], v[114:115], v[114:115]
	v_mov_b32_e32 v116, v81
	v_mov_b32_e32 v117, v85
	v_pk_fma_f32 v[112:113], v[112:113], v[112:113], v[114:115]
	v_mov_b32_e32 v114, v80
	v_mov_b32_e32 v115, v84
	v_pk_mul_f32 v[116:117], v[116:117], v[116:117]
	s_add_i32 s10, s10, s82
	v_pk_fma_f32 v[114:115], v[114:115], v[114:115], v[116:117]
	v_pk_mul_f32 v[116:117], v[94:95], v[94:95]
	v_pk_add_f32 v[112:113], v[112:113], v[114:115]
	v_pk_mul_f32 v[114:115], v[92:93], v[92:93]
	v_pk_add_f32 v[112:113], v[112:113], v[112:113] op_sel:[0,1] op_sel_hi:[1,0]
	v_pk_mov_b32 v[118:119], v[116:117], v[114:115] op_sel:[1,0]
	v_mov_b32_e32 v117, v115
	v_pk_add_f32 v[114:115], v[118:119], v[116:117]
	v_mul_f32_e32 v116, v106, v106
	v_mul_f32_e32 v117, v107, v107
	v_pk_add_f32 v[114:115], v[114:115], v[114:115] op_sel:[0,1] op_sel_hi:[1,0]
	v_mov_b32_e32 v113, v116
	v_mov_b32_e32 v115, v117
	v_pk_add_f32 v[112:113], v[112:113], v[114:115]
	v_mul_f32_e32 v114, v103, v103
	v_mul_f32_e32 v116, v101, v101
	v_mul_f32_e32 v118, v104, v104
	v_mul_f32_e32 v119, v105, v105
	v_pk_fma_f32 v[114:115], v[102:103], v[102:103], v[114:115] op_sel_hi:[1,1,0]
	v_pk_fma_f32 v[116:117], v[100:101], v[100:101], v[116:117] op_sel_hi:[1,1,0]
	v_mov_b32_e32 v115, v118
	v_mov_b32_e32 v117, v119
	v_pk_add_f32 v[114:115], v[114:115], v[116:117]
	v_pk_mul_f32 v[116:117], v[108:109], v[108:109]
	v_pk_add_f32 v[112:113], v[112:113], v[114:115]
	v_pk_mul_f32 v[114:115], v[110:111], v[110:111]
	v_pk_add_f32 v[112:113], v[112:113], v[112:113] op_sel:[0,1] op_sel_hi:[1,0]
	v_pk_mov_b32 v[118:119], v[116:117], v[114:115] op_sel:[1,0]
	v_mov_b32_e32 v117, v115
	v_pk_add_f32 v[114:115], v[118:119], v[116:117]
	v_mul_f32_e32 v116, v88, v88
	v_mul_f32_e32 v117, v89, v89
	v_pk_add_f32 v[114:115], v[114:115], v[114:115] op_sel:[0,1] op_sel_hi:[1,0]
	v_mov_b32_e32 v113, v116
	v_mov_b32_e32 v115, v117
	v_pk_add_f32 v[112:113], v[112:113], v[114:115]
	v_mul_f32_e32 v114, v97, v97
	v_mul_f32_e32 v116, v99, v99
	v_mul_f32_e32 v118, v90, v90
	v_mul_f32_e32 v119, v91, v91
	v_pk_fma_f32 v[114:115], v[96:97], v[96:97], v[114:115] op_sel_hi:[1,1,0]
	v_pk_fma_f32 v[116:117], v[98:99], v[98:99], v[116:117] op_sel_hi:[1,1,0]
	v_mov_b32_e32 v115, v118
	v_mov_b32_e32 v117, v119
	v_pk_add_f32 v[114:115], v[114:115], v[116:117]
	v_bfe_u32 v116, v81, 16, 1
	v_pk_add_f32 v[112:113], v[112:113], v[114:115]
	v_add3_u32 v116, v81, v116, s8
	v_add_f32_e32 v112, v112, v113
	ds_bpermute_b32 v113, v178, v112
	s_add_i32 s1, s10, 0x2000
	s_add_i32 s0, s0, s92
	s_cmpk_lt_i32 s1, 0x2400
	s_waitcnt lgkmcnt(0)
	v_add_f32_e32 v112, v112, v113
	ds_bpermute_b32 v113, v179, v112
	s_waitcnt lgkmcnt(0)
	v_add_f32_e32 v112, v112, v113
	ds_bpermute_b32 v113, v180, v112
	s_waitcnt lgkmcnt(0)
	v_add_f32_e32 v112, v112, v113
	ds_bpermute_b32 v113, v181, v112
	s_waitcnt lgkmcnt(0)
	v_add_f32_e32 v112, v112, v113
	ds_bpermute_b32 v113, v182, v112
	s_waitcnt lgkmcnt(0)
	v_add_f32_e32 v114, v112, v113
	v_bfe_u32 v112, v82, 16, 1
	v_add3_u32 v112, v82, v112, s8
	v_bfe_u32 v113, v83, 16, 1
	v_lshrrev_b32_e32 v112, 16, v112
	v_add3_u32 v113, v83, v113, s8
	v_and_or_b32 v112, v113, s58, v112
	v_bfe_u32 v113, v80, 16, 1
	v_add3_u32 v113, v80, v113, s8
	v_lshrrev_b32_e32 v113, 16, v113
	v_and_or_b32 v113, v116, s58, v113
	global_store_dwordx2 v[78:79], v[112:113], off offset:-3584
	v_bfe_u32 v112, v86, 16, 1
	v_add3_u32 v112, v86, v112, s8
	v_bfe_u32 v113, v87, 16, 1
	v_lshrrev_b32_e32 v112, 16, v112
	v_add3_u32 v113, v87, v113, s8
	v_and_or_b32 v112, v113, s58, v112
	v_bfe_u32 v113, v84, 16, 1
	v_add3_u32 v113, v84, v113, s8
	v_bfe_u32 v116, v85, 16, 1
	v_lshrrev_b32_e32 v113, 16, v113
	v_add3_u32 v116, v85, v116, s8
	v_and_or_b32 v113, v116, s58, v113
	global_store_dwordx2 v[78:79], v[112:113], off offset:-3072
	v_bfe_u32 v112, v94, 16, 1
	v_add3_u32 v112, v94, v112, s8
	v_bfe_u32 v113, v95, 16, 1
	v_lshrrev_b32_e32 v112, 16, v112
	v_add3_u32 v113, v95, v113, s8
	v_and_or_b32 v112, v113, s58, v112
	v_bfe_u32 v113, v92, 16, 1
	v_add3_u32 v113, v92, v113, s8
	v_bfe_u32 v116, v93, 16, 1
	v_lshrrev_b32_e32 v113, 16, v113
	v_add3_u32 v116, v93, v116, s8
	v_and_or_b32 v113, v116, s58, v113
	global_store_dwordx2 v[78:79], v[112:113], off offset:-2560
	v_bfe_u32 v112, v102, 16, 1
	v_add3_u32 v112, v102, v112, s8
	v_bfe_u32 v113, v103, 16, 1
	v_lshrrev_b32_e32 v112, 16, v112
	v_add3_u32 v113, v103, v113, s8
	v_and_or_b32 v112, v113, s58, v112
	v_bfe_u32 v113, v100, 16, 1
	v_add3_u32 v113, v100, v113, s8
	v_bfe_u32 v116, v101, 16, 1
	v_lshrrev_b32_e32 v113, 16, v113
	v_add3_u32 v116, v101, v116, s8
	v_and_or_b32 v113, v116, s58, v113
	global_store_dwordx2 v[78:79], v[112:113], off offset:-2048
	v_bfe_u32 v112, v106, 16, 1
	v_add3_u32 v112, v106, v112, s8
	v_bfe_u32 v113, v107, 16, 1
	v_lshrrev_b32_e32 v112, 16, v112
	v_add3_u32 v113, v107, v113, s8
	v_and_or_b32 v112, v113, s58, v112
	v_bfe_u32 v113, v104, 16, 1
	v_add3_u32 v113, v104, v113, s8
	v_bfe_u32 v116, v105, 16, 1
	v_lshrrev_b32_e32 v113, 16, v113
	v_add3_u32 v116, v105, v116, s8
	v_and_or_b32 v113, v116, s58, v113
	global_store_dwordx2 v[78:79], v[112:113], off offset:-1536
	v_bfe_u32 v112, v108, 16, 1
	v_add3_u32 v112, v108, v112, s8
	v_bfe_u32 v113, v109, 16, 1
	v_lshrrev_b32_e32 v112, 16, v112
	v_add3_u32 v113, v109, v113, s8
	v_and_or_b32 v112, v113, s58, v112
	v_bfe_u32 v113, v110, 16, 1
	v_add3_u32 v113, v110, v113, s8
	v_bfe_u32 v116, v111, 16, 1
	v_lshrrev_b32_e32 v113, 16, v113
	v_add3_u32 v116, v111, v116, s8
	v_and_or_b32 v113, v116, s58, v113
	global_store_dwordx2 v[78:79], v[112:113], off offset:-1024
	v_bfe_u32 v112, v96, 16, 1
	v_add3_u32 v112, v96, v112, s8
	v_bfe_u32 v113, v97, 16, 1
	v_lshrrev_b32_e32 v112, 16, v112
	v_add3_u32 v113, v97, v113, s8
	v_and_or_b32 v112, v113, s58, v112
	v_bfe_u32 v113, v98, 16, 1
	v_add3_u32 v113, v98, v113, s8
	v_bfe_u32 v116, v99, 16, 1
	v_lshrrev_b32_e32 v113, 16, v113
	v_add3_u32 v116, v99, v116, s8
	v_and_or_b32 v113, v116, s58, v113
	global_store_dwordx2 v[78:79], v[112:113], off offset:-512
	v_bfe_u32 v112, v88, 16, 1
	v_add3_u32 v112, v88, v112, s8
	v_bfe_u32 v113, v89, 16, 1
	ds_bpermute_b32 v115, v183, v114
	v_lshrrev_b32_e32 v112, 16, v112
	v_add3_u32 v113, v89, v113, s8
	v_and_or_b32 v112, v113, s58, v112
	v_bfe_u32 v113, v90, 16, 1
	v_add3_u32 v113, v90, v113, s8
	v_bfe_u32 v116, v91, 16, 1
	v_lshrrev_b32_e32 v113, 16, v113
	v_add3_u32 v116, v91, v116, s8
	v_and_or_b32 v113, v116, s58, v113
	global_store_dwordx2 v[78:79], v[112:113], off
	s_waitcnt lgkmcnt(0)
; __device__ __forceinline__ unsigned pk2(float lo, float hi) { return f2bf(lo) | (f2bf(hi) << 16); }
; template <int MODE>
; __device__ __forceinline__ void norm_apply(f32x4 (&v)[8], bf16_t* xcopy, const f32x4 (&GG)[8], const f32x4 (&SS)[8], bf16_t* obf, float* of32, int lane, const float* slabrow = nullptr, const float* gate = nullptr) {
;     ...
;     const float rstd = rsqrtf(wave_sum(ss) * (1.f / D) + 1e-6f);
;     if (xcopy) {
; #pragma unroll
;         for (int j = 0; j < 8; ++j) { u32x2 w; w.x = pk2(v[j].x, v[j].y); w.y = pk2(v[j].z, v[j].w); ((u32x2*)xcopy)[lane + 64 * j] = w; } }
; #pragma unroll
;     for (int j = 0; j < 8; ++j) { const int c4 = lane + 64 * j;
;         f32x4 h = v[j] * rstd * GG[j];
;         if (MODE == 0) { h = h + SS[j]; u32x2 w; w.x = pk2(h.x, h.y); w.y = pk2(h.z, h.w); ((u32x2*)obf)[c4] = w; }
;         else ((f32x4*)of32)[c4] = h; }
	v_add_f32_e32 v78, v114, v115
	v_fmamk_f32 v78, v78, 0x3a000000, v238
	v_cmp_gt_f32_e32 vcc, s70, v78
	v_mul_f32_e32 v79, 0x4b800000, v78
	s_nop 0
	v_cndmask_b32_e32 v78, v78, v79, vcc
	v_rsq_f32_e32 v78, v78
	s_nop 0
	v_mul_f32_e32 v79, 0x45800000, v78
	v_cndmask_b32_e32 v78, v78, v79, vcc
	v_pk_mul_f32 v[82:83], v[82:83], v[78:79] op_sel_hi:[1,0]
	v_pk_mul_f32 v[80:81], v[80:81], v[78:79] op_sel_hi:[1,0]
	v_pk_fma_f32 v[82:83], v[36:37], v[82:83], v[2:3]
	v_pk_fma_f32 v[80:81], v[34:35], v[80:81], v[4:5]
	v_bfe_u32 v79, v82, 16, 1
	v_add3_u32 v79, v82, v79, s8
	v_bfe_u32 v82, v83, 16, 1
	v_lshrrev_b32_e32 v79, 16, v79
	v_add3_u32 v82, v83, v82, s8
	v_and_or_b32 v82, v82, s58, v79
	v_bfe_u32 v79, v80, 16, 1
	v_add3_u32 v79, v80, v79, s8
	v_bfe_u32 v80, v81, 16, 1
	v_lshrrev_b32_e32 v79, 16, v79
	v_add3_u32 v80, v81, v80, s8
	v_and_or_b32 v83, v80, s58, v79
	v_pk_mul_f32 v[80:81], v[86:87], v[78:79] op_sel_hi:[1,0]
	global_store_dwordx2 v[76:77], v[82:83], off offset:-3584
	v_pk_fma_f32 v[80:81], v[40:41], v[80:81], v[6:7]
	v_pk_mul_f32 v[82:83], v[84:85], v[78:79] op_sel_hi:[1,0]
	v_bfe_u32 v79, v80, 16, 1
	v_add3_u32 v79, v80, v79, s8
	v_bfe_u32 v80, v81, 16, 1
	v_pk_fma_f32 v[82:83], v[38:39], v[82:83], v[8:9]
	v_lshrrev_b32_e32 v79, 16, v79
	v_add3_u32 v80, v81, v80, s8
	v_and_or_b32 v80, v80, s58, v79
	v_bfe_u32 v79, v82, 16, 1
	v_add3_u32 v79, v82, v79, s8
	v_bfe_u32 v81, v83, 16, 1
	v_lshrrev_b32_e32 v79, 16, v79
	v_add3_u32 v81, v83, v81, s8
	v_and_or_b32 v81, v81, s58, v79
	global_store_dwordx2 v[76:77], v[80:81], off offset:-3072
	v_pk_mul_f32 v[80:81], v[94:95], v[78:79] op_sel_hi:[1,0]
	v_pk_mul_f32 v[82:83], v[92:93], v[78:79] op_sel_hi:[1,0]
	v_pk_fma_f32 v[80:81], v[44:45], v[80:81], v[10:11]
	v_pk_fma_f32 v[82:83], v[42:43], v[82:83], v[12:13]
	v_bfe_u32 v79, v80, 16, 1
	v_add3_u32 v79, v80, v79, s8
	v_bfe_u32 v80, v81, 16, 1
	v_lshrrev_b32_e32 v79, 16, v79
	v_add3_u32 v80, v81, v80, s8
	v_and_or_b32 v80, v80, s58, v79
	v_bfe_u32 v79, v82, 16, 1
	v_add3_u32 v79, v82, v79, s8
	v_bfe_u32 v81, v83, 16, 1
	v_lshrrev_b32_e32 v79, 16, v79
	v_add3_u32 v81, v83, v81, s8
	v_and_or_b32 v81, v81, s58, v79
	global_store_dwordx2 v[76:77], v[80:81], off offset:-2560
	v_pk_mul_f32 v[80:81], v[102:103], v[78:79] op_sel_hi:[1,0]
	v_pk_mul_f32 v[82:83], v[100:101], v[78:79] op_sel_hi:[1,0]
	v_pk_fma_f32 v[80:81], v[48:49], v[80:81], v[14:15]
	v_pk_fma_f32 v[82:83], v[46:47], v[82:83], v[16:17]
	v_bfe_u32 v79, v80, 16, 1
	v_add3_u32 v79, v80, v79, s8
	v_bfe_u32 v80, v81, 16, 1
	v_lshrrev_b32_e32 v79, 16, v79
	v_add3_u32 v80, v81, v80, s8
	v_and_or_b32 v80, v80, s58, v79
	v_bfe_u32 v79, v82, 16, 1
	v_add3_u32 v79, v82, v79, s8
	v_bfe_u32 v81, v83, 16, 1
	v_lshrrev_b32_e32 v79, 16, v79
	v_add3_u32 v81, v83, v81, s8
	v_and_or_b32 v81, v81, s58, v79
	global_store_dwordx2 v[76:77], v[80:81], off offset:-2048
	v_pk_mul_f32 v[80:81], v[106:107], v[78:79] op_sel_hi:[1,0]
	v_pk_mul_f32 v[82:83], v[104:105], v[78:79] op_sel_hi:[1,0]
	v_pk_fma_f32 v[80:81], v[52:53], v[80:81], v[18:19]
	v_pk_fma_f32 v[82:83], v[50:51], v[82:83], v[20:21]
	v_bfe_u32 v79, v80, 16, 1
	v_add3_u32 v79, v80, v79, s8
	v_bfe_u32 v80, v81, 16, 1
	v_lshrrev_b32_e32 v79, 16, v79
	v_add3_u32 v80, v81, v80, s8
	v_and_or_b32 v80, v80, s58, v79
	v_bfe_u32 v79, v82, 16, 1
	v_add3_u32 v79, v82, v79, s8
	v_bfe_u32 v81, v83, 16, 1
	v_lshrrev_b32_e32 v79, 16, v79
	v_add3_u32 v81, v83, v81, s8
	v_and_or_b32 v81, v81, s58, v79
	global_store_dwordx2 v[76:77], v[80:81], off offset:-1536
	v_pk_mul_f32 v[80:81], v[108:109], v[78:79] op_sel_hi:[1,0]
	v_pk_mul_f32 v[82:83], v[110:111], v[78:79] op_sel_hi:[1,0]
	v_pk_fma_f32 v[80:81], v[56:57], v[80:81], v[22:23]
	v_pk_fma_f32 v[82:83], v[54:55], v[82:83], v[24:25]
	v_bfe_u32 v79, v80, 16, 1
	v_add3_u32 v79, v80, v79, s8
	v_bfe_u32 v80, v81, 16, 1
	v_lshrrev_b32_e32 v79, 16, v79
	v_add3_u32 v80, v81, v80, s8
	v_and_or_b32 v80, v80, s58, v79
	v_bfe_u32 v79, v82, 16, 1
	v_add3_u32 v79, v82, v79, s8
	v_bfe_u32 v81, v83, 16, 1
	v_lshrrev_b32_e32 v79, 16, v79
	v_add3_u32 v81, v83, v81, s8
	v_and_or_b32 v81, v81, s58, v79
	global_store_dwordx2 v[76:77], v[80:81], off offset:-1024
	v_pk_mul_f32 v[80:81], v[96:97], v[78:79] op_sel_hi:[1,0]
	v_pk_mul_f32 v[82:83], v[98:99], v[78:79] op_sel_hi:[1,0]
	v_pk_fma_f32 v[80:81], v[60:61], v[80:81], v[26:27]
	v_pk_fma_f32 v[82:83], v[58:59], v[82:83], v[28:29]
	v_bfe_u32 v79, v80, 16, 1
	v_add3_u32 v79, v80, v79, s8
	v_bfe_u32 v80, v81, 16, 1
	v_lshrrev_b32_e32 v79, 16, v79
	v_add3_u32 v80, v81, v80, s8
	v_and_or_b32 v80, v80, s58, v79
	v_bfe_u32 v79, v82, 16, 1
	v_add3_u32 v79, v82, v79, s8
	v_bfe_u32 v81, v83, 16, 1
	v_lshrrev_b32_e32 v79, 16, v79
	v_add3_u32 v81, v83, v81, s8
	v_and_or_b32 v81, v81, s58, v79
	global_store_dwordx2 v[76:77], v[80:81], off offset:-512
	v_pk_mul_f32 v[80:81], v[88:89], v[78:79] op_sel_hi:[1,0]
	v_pk_mul_f32 v[78:79], v[90:91], v[78:79] op_sel_hi:[1,0]
	v_pk_fma_f32 v[80:81], v[64:65], v[80:81], v[30:31]
	v_pk_fma_f32 v[78:79], v[62:63], v[78:79], v[32:33]
	v_bfe_u32 v82, v80, 16, 1
	v_add3_u32 v80, v80, v82, s8
	v_bfe_u32 v82, v81, 16, 1
	v_lshrrev_b32_e32 v80, 16, v80
	v_add3_u32 v81, v81, v82, s8
	v_and_or_b32 v80, v81, s58, v80
	v_bfe_u32 v81, v78, 16, 1
	v_add3_u32 v78, v78, v81, s8
	v_bfe_u32 v81, v79, 16, 1
	v_lshrrev_b32_e32 v78, 16, v78
	v_add3_u32 v79, v79, v81, s8
	v_and_or_b32 v81, v79, s58, v78
	global_store_dwordx2 v[76:77], v[80:81], off
	v_lshl_add_u64 v[76:77], v[76:77], 0, s[88:89]
	s_cbranch_scc1 .LBB9_1331

; __device__ __forceinline__ void norm_load(const bf16_t* xrow, f32x4 (&v)[8], int lane) {
;     const u32x2* xr = (const u32x2*)xrow + lane; u32x2 r[8];
; #pragma unroll
;     for (int j = 0; j < 8; ++j) r[j] = xr[64 * j];
; #pragma unroll
;     for (int j = 0; j < 8; ++j) v[j] = (f32x4){bf_lo(r[j].x), bf_hi(r[j].x), bf_lo(r[j].y), bf_hi(r[j].y)};
; }
; template <int MODE>
; __device__ __forceinline__ void norm_apply(f32x4 (&v)[8], bf16_t* xcopy, const f32x4 (&GG)[8], const f32x4 (&SS)[8], bf16_t* obf, float* of32, int lane, const float* slabrow = nullptr, const float* gate = nullptr) {
;     float ss = 0.f;
;     if (slabrow) {
; #pragma unroll
;         for (int jh = 0; jh < 2; ++jh) { u32x2 p[4][8];
; #pragma unroll
;             for (int jj = 0; jj < 4; ++jj) { const int j = jh * 4 + jj; const u32x2* sp = (const u32x2*)((const bf16_t*)slabrow + (size_t)j * 8 * 65536) + lane;
; #pragma unroll
;                 for (int s = 0; s < 8; ++s) p[jj][s] = sp[(size_t)s * 16384]; }
.LBB9_1724:
	s_ashr_i32 s4, s14, 8
	s_ashr_i32 s5, s4, 31
	s_lshl_b64 s[4:5], s[4:5], 23
	s_add_u32 s3, s22, s4
	s_addc_u32 s5, s23, s5
	s_and_b32 s4, s10, 0xff00
	s_lshl_b32 s4, s4, 1
	s_add_u32 s4, s3, s4
	v_add_co_u32_e32 v78, vcc, 0xfb800000, v76
	s_addc_u32 s5, s5, 0
	s_nop 0
	v_addc_co_u32_e32 v79, vcc, -1, v77, vcc
	v_lshl_add_u64 v[104:105], s[4:5], 0, v[186:187]
	v_add_co_u32_e32 v84, vcc, s51, v104
	global_load_dwordx2 v[108:109], v[78:79], off offset:-3584
	global_load_dwordx2 v[106:107], v[78:79], off offset:-3072
	global_load_dwordx2 v[98:99], v[78:79], off offset:-2560
	global_load_dwordx2 v[96:97], v[78:79], off offset:-2048
	global_load_dwordx2 v[90:91], v[78:79], off offset:-1536
	global_load_dwordx2 v[88:89], v[78:79], off offset:-1024
	global_load_dwordx2 v[82:83], v[78:79], off offset:-512
	global_load_dwordx2 v[80:81], v[78:79], off
	v_addc_co_u32_e32 v85, vcc, 0, v105, vcc
	global_load_dwordx2 v[174:175], v186, s[4:5]
	global_load_dwordx2 v[176:177], v[84:85], off
	v_add_co_u32_e32 v84, vcc, s6, v104
	v_addc_co_u32_e32 v85, vcc, 0, v105, vcc
	global_load_dwordx2 v[164:165], v[84:85], off
	v_add_co_u32_e32 v84, vcc, s59, v104
	s_nop 0
	v_addc_co_u32_e32 v85, vcc, 0, v105, vcc
	global_load_dwordx2 v[162:163], v[84:85], off
	v_add_co_u32_e32 v84, vcc, s7, v104
	s_nop 0
	v_addc_co_u32_e32 v85, vcc, 0, v105, vcc
	global_load_dwordx2 v[170:171], v[84:85], off
	v_add_co_u32_e32 v84, vcc, s37, v104
	s_nop 0
	v_addc_co_u32_e32 v85, vcc, 0, v105, vcc
	global_load_dwordx2 v[166:167], v[84:85], off
	v_add_co_u32_e32 v84, vcc, s2, v104
	v_addc_co_u32_e32 v85, vcc, 0, v105, vcc
	global_load_dwordx2 v[168:169], v[84:85], off
	v_add_co_u32_e32 v84, vcc, s82, v104
	s_nop 0
	v_addc_co_u32_e32 v85, vcc, 0, v105, vcc
	global_load_dwordx2 v[172:173], v[84:85], off
	v_add_co_u32_e32 v84, vcc, s60, v104
	s_nop 0
	v_addc_co_u32_e32 v85, vcc, 0, v105, vcc
	global_load_dwordx2 v[156:157], v[84:85], off
	v_add_co_u32_e32 v84, vcc, s70, v104
	s_nop 0
	v_addc_co_u32_e32 v85, vcc, 0, v105, vcc
	global_load_dwordx2 v[154:155], v[84:85], off
	v_add_co_u32_e32 v84, vcc, s61, v104
	v_addc_co_u32_e32 v85, vcc, 0, v105, vcc
	global_load_dwordx2 v[152:153], v[84:85], off
	v_add_co_u32_e32 v84, vcc, s52, v104
	s_nop 0
	v_addc_co_u32_e32 v85, vcc, 0, v105, vcc
	global_load_dwordx2 v[148:149], v[84:85], off
	v_add_co_u32_e32 v84, vcc, s17, v104
	s_nop 0
	v_addc_co_u32_e32 v85, vcc, 0, v105, vcc
	global_load_dwordx2 v[150:151], v[84:85], off
	v_add_co_u32_e32 v84, vcc, s43, v104
	s_nop 0
	v_addc_co_u32_e32 v85, vcc, 0, v105, vcc
	v_add_co_u32_e32 v86, vcc, s62, v104
	global_load_dwordx2 v[84:85], v[84:85], off
	s_nop 0
	v_addc_co_u32_e32 v87, vcc, 0, v105, vcc
	v_add_co_u32_e32 v92, vcc, s66, v104
	global_load_dwordx2 v[86:87], v[86:87], off
	s_nop 0
	v_addc_co_u32_e32 v93, vcc, 0, v105, vcc
	global_load_dwordx2 v[146:147], v[92:93], off
	v_add_co_u32_e32 v92, vcc, s0, v104
	v_addc_co_u32_e32 v93, vcc, 0, v105, vcc
	global_load_dwordx2 v[132:133], v[92:93], off
	v_add_co_u32_e32 v92, vcc, s69, v104
	s_nop 0
	v_addc_co_u32_e32 v93, vcc, 0, v105, vcc
	global_load_dwordx2 v[130:131], v[92:93], off
	v_add_co_u32_e32 v92, vcc, s53, v104
	s_nop 0
	v_addc_co_u32_e32 v93, vcc, 0, v105, vcc
	v_add_co_u32_e32 v94, vcc, s54, v104
	global_load_dwordx2 v[92:93], v[92:93], off
	s_nop 0
	v_addc_co_u32_e32 v95, vcc, 0, v105, vcc
	v_add_co_u32_e32 v100, vcc, s55, v104
	global_load_dwordx2 v[94:95], v[94:95], off
	s_nop 0
	v_addc_co_u32_e32 v101, vcc, 0, v105, vcc
	global_load_dwordx2 v[138:139], v[100:101], off
	v_add_co_u32_e32 v100, vcc, s57, v104
	s_nop 0
	v_addc_co_u32_e32 v101, vcc, 0, v105, vcc
	global_load_dwordx2 v[134:135], v[100:101], off
	v_add_co_u32_e32 v100, vcc, s65, v104
	v_addc_co_u32_e32 v101, vcc, 0, v105, vcc
	global_load_dwordx2 v[136:137], v[100:101], off
	v_add_co_u32_e32 v100, vcc, s83, v104
	s_nop 0
	v_addc_co_u32_e32 v101, vcc, 0, v105, vcc
	global_load_dwordx2 v[140:141], v[100:101], off
	v_add_co_u32_e32 v100, vcc, s16, v104
	s_nop 0
	v_addc_co_u32_e32 v101, vcc, 0, v105, vcc
	global_load_dwordx2 v[122:123], v[100:101], off
	v_add_co_u32_e32 v100, vcc, s76, v104
	s_nop 0
	v_addc_co_u32_e32 v101, vcc, 0, v105, vcc
	global_load_dwordx2 v[118:119], v[100:101], off
	v_add_co_u32_e32 v100, vcc, s33, v104
	v_addc_co_u32_e32 v101, vcc, 0, v105, vcc
	global_load_dwordx2 v[114:115], v[100:101], off
	v_add_co_u32_e32 v100, vcc, s30, v104
	s_nop 0
	v_addc_co_u32_e32 v101, vcc, 0, v105, vcc
	v_add_co_u32_e32 v102, vcc, s78, v104
	global_load_dwordx2 v[100:101], v[100:101], off
	s_nop 0
	v_addc_co_u32_e32 v103, vcc, 0, v105, vcc
	global_load_dwordx2 v[124:125], v[102:103], off
	v_add_co_u32_e32 v102, vcc, s85, v104
	v_addc_co_u32_e32 v103, vcc, 0, v105, vcc
	global_load_dwordx2 v[116:117], v[102:103], off
	v_add_co_u32_e32 v102, vcc, s80, v104
	s_nop 0
	v_addc_co_u32_e32 v103, vcc, 0, v105, vcc
	v_add_co_u32_e32 v110, vcc, s94, v104
	global_load_dwordx2 v[102:103], v[102:103], off
	s_nop 0
	v_addc_co_u32_e32 v111, vcc, 0, v105, vcc
	global_load_dwordx2 v[126:127], v[110:111], off
	s_waitcnt vmcnt(39)
	v_lshlrev_b32_e32 v184, 16, v108
	v_and_b32_e32 v185, 0xffff0000, v108
	v_lshlrev_b32_e32 v188, 16, v109
	v_and_b32_e32 v189, 0xffff0000, v109
	s_waitcnt vmcnt(38)
	v_lshlrev_b32_e32 v158, 16, v106
	v_and_b32_e32 v159, 0xffff0000, v106
	v_lshlrev_b32_e32 v160, 16, v107
	v_and_b32_e32 v161, 0xffff0000, v107
	s_waitcnt vmcnt(37)
	v_lshlrev_b32_e32 v142, 16, v98
	v_and_b32_e32 v143, 0xffff0000, v98
	v_lshlrev_b32_e32 v144, 16, v99
	v_and_b32_e32 v145, 0xffff0000, v99
	s_waitcnt vmcnt(36)
; __device__ __forceinline__ void norm_load(const bf16_t* xrow, f32x4 (&v)[8], int lane) {
;     ...
;     for (int j = 0; j < 8; ++j) v[j] = (f32x4){bf_lo(r[j].x), bf_hi(r[j].x), bf_lo(r[j].y), bf_hi(r[j].y)};
; template <int MODE>
; __device__ __forceinline__ void norm_apply(f32x4 (&v)[8], bf16_t* xcopy, const f32x4 (&GG)[8], const f32x4 (&SS)[8], bf16_t* obf, float* of32, int lane, const float* slabrow = nullptr, const float* gate = nullptr) {
;     ...
;         for (int jh = 0; jh < 2; ++jh) { u32x2 p[4][8];
; #pragma unroll
;             for (int jj = 0; jj < 4; ++jj) { const int j = jh * 4 + jj; const u32x2* sp = (const u32x2*)((const bf16_t*)slabrow + (size_t)j * 8 * 65536) + lane;
; #pragma unroll
;                 for (int s = 0; s < 8; ++s) p[jj][s] = sp[(size_t)s * 16384]; }
;             __builtin_amdgcn_sched_barrier(0);
; #pragma unroll
;             for (int jj = 0; jj < 4; ++jj) { const int j = jh * 4 + jj; const f32x4 gt = ((const f32x4*)gate)[lane + 64 * j];
;                 f32x4 a = {bf_lo(p[jj][0].x), bf_hi(p[jj][0].x), bf_lo(p[jj][0].y), bf_hi(p[jj][0].y)};
; #pragma unroll
;                 for (int s = 1; s < 8; ++s) a += (f32x4){bf_lo(p[jj][s].x), bf_hi(p[jj][s].x), bf_lo(p[jj][s].y), bf_hi(p[jj][s].y)};
;                 v[j] += gt * a; }
	v_lshlrev_b32_e32 v120, 16, v96
	v_and_b32_e32 v121, 0xffff0000, v96
	v_lshlrev_b32_e32 v128, 16, v97
	v_and_b32_e32 v129, 0xffff0000, v97
	s_waitcnt vmcnt(35)
	v_lshlrev_b32_e32 v106, 16, v90
	v_and_b32_e32 v107, 0xffff0000, v90
	v_lshlrev_b32_e32 v112, 16, v91
	v_and_b32_e32 v113, 0xffff0000, v91
	s_waitcnt vmcnt(34)
	v_lshlrev_b32_e32 v108, 16, v88
	v_and_b32_e32 v109, 0xffff0000, v88
	s_waitcnt vmcnt(33)
	v_lshlrev_b32_e32 v96, 16, v82
	v_and_b32_e32 v97, 0xffff0000, v82
	v_lshlrev_b32_e32 v110, 16, v89
	v_and_b32_e32 v111, 0xffff0000, v89
	v_lshlrev_b32_e32 v98, 16, v83
	v_and_b32_e32 v99, 0xffff0000, v83
	s_waitcnt vmcnt(32)
	v_lshlrev_b32_e32 v88, 16, v80
	v_and_b32_e32 v89, 0xffff0000, v80
	v_lshlrev_b32_e32 v90, 16, v81
	v_and_b32_e32 v91, 0xffff0000, v81
	global_load_dwordx4 v[190:193], v[66:67], off
	s_waitcnt vmcnt(32)
	v_lshlrev_b32_e32 v80, 16, v174
	v_and_b32_e32 v81, 0xffff0000, v174
	v_lshlrev_b32_e32 v82, 16, v175
	v_and_b32_e32 v83, 0xffff0000, v175
	s_waitcnt vmcnt(31)
	v_lshlrev_b32_e32 v174, 16, v176
	v_and_b32_e32 v175, 0xffff0000, v176
	v_lshlrev_b32_e32 v176, 16, v177
	v_and_b32_e32 v177, 0xffff0000, v177
	v_pk_add_f32 v[80:81], v[80:81], v[174:175]
	v_pk_add_f32 v[82:83], v[82:83], v[176:177]
	s_waitcnt vmcnt(30)
	v_lshlrev_b32_e32 v174, 16, v164
	v_and_b32_e32 v175, 0xffff0000, v164
	v_lshlrev_b32_e32 v164, 16, v165
	v_and_b32_e32 v165, 0xffff0000, v165
	v_pk_add_f32 v[82:83], v[82:83], v[164:165]
	v_pk_add_f32 v[80:81], v[80:81], v[174:175]
	s_waitcnt vmcnt(29)
	v_lshlrev_b32_e32 v164, 16, v162
	v_and_b32_e32 v165, 0xffff0000, v162
	v_lshlrev_b32_e32 v162, 16, v163
	v_and_b32_e32 v163, 0xffff0000, v163
	v_pk_add_f32 v[80:81], v[80:81], v[164:165]
	v_pk_add_f32 v[82:83], v[82:83], v[162:163]
	s_waitcnt vmcnt(28)
	v_lshlrev_b32_e32 v162, 16, v170
	v_and_b32_e32 v163, 0xffff0000, v170
	v_lshlrev_b32_e32 v164, 16, v171
	v_and_b32_e32 v165, 0xffff0000, v171
	v_pk_add_f32 v[82:83], v[82:83], v[164:165]
	v_pk_add_f32 v[80:81], v[80:81], v[162:163]
	s_waitcnt vmcnt(27)
	v_lshlrev_b32_e32 v162, 16, v166
	v_and_b32_e32 v163, 0xffff0000, v166
	v_lshlrev_b32_e32 v164, 16, v167
	v_and_b32_e32 v165, 0xffff0000, v167
	v_pk_add_f32 v[80:81], v[80:81], v[162:163]
	v_pk_add_f32 v[82:83], v[82:83], v[164:165]
	s_waitcnt vmcnt(26)
	v_lshlrev_b32_e32 v162, 16, v168
	v_and_b32_e32 v163, 0xffff0000, v168
	v_lshlrev_b32_e32 v164, 16, v169
	v_and_b32_e32 v165, 0xffff0000, v169
	s_waitcnt vmcnt(24)
	v_lshlrev_b32_e32 v166, 16, v156
	v_and_b32_e32 v167, 0xffff0000, v156
	v_lshlrev_b32_e32 v156, 16, v157
	v_and_b32_e32 v157, 0xffff0000, v157
	s_waitcnt vmcnt(23)
	v_lshlrev_b32_e32 v168, 16, v154
	v_and_b32_e32 v169, 0xffff0000, v154
	v_lshlrev_b32_e32 v154, 16, v155
	v_and_b32_e32 v155, 0xffff0000, v155
	v_pk_add_f32 v[166:167], v[166:167], v[168:169]
	v_pk_add_f32 v[154:155], v[156:157], v[154:155]
	s_waitcnt vmcnt(22)
	v_lshlrev_b32_e32 v156, 16, v152
	v_and_b32_e32 v157, 0xffff0000, v152
	v_lshlrev_b32_e32 v152, 16, v153
	v_and_b32_e32 v153, 0xffff0000, v153
	v_pk_add_f32 v[152:153], v[154:155], v[152:153]
	v_pk_add_f32 v[154:155], v[166:167], v[156:157]
	s_waitcnt vmcnt(21)
	v_lshlrev_b32_e32 v156, 16, v148
	v_and_b32_e32 v157, 0xffff0000, v148
	v_lshlrev_b32_e32 v148, 16, v149
	v_and_b32_e32 v149, 0xffff0000, v149
	v_pk_add_f32 v[154:155], v[154:155], v[156:157]
	v_pk_add_f32 v[148:149], v[152:153], v[148:149]
	s_waitcnt vmcnt(20)
	v_lshlrev_b32_e32 v152, 16, v150
	v_and_b32_e32 v153, 0xffff0000, v150
	v_lshlrev_b32_e32 v150, 16, v151
	v_and_b32_e32 v151, 0xffff0000, v151
	v_pk_add_f32 v[148:149], v[148:149], v[150:151]
	v_pk_add_f32 v[150:151], v[154:155], v[152:153]
	s_waitcnt vmcnt(19)
	v_lshlrev_b32_e32 v152, 16, v84
	v_and_b32_e32 v153, 0xffff0000, v84
	v_lshlrev_b32_e32 v84, 16, v85
	v_and_b32_e32 v85, 0xffff0000, v85
	v_pk_add_f32 v[150:151], v[150:151], v[152:153]
	v_pk_add_f32 v[84:85], v[148:149], v[84:85]
	s_waitcnt vmcnt(18)
	v_lshlrev_b32_e32 v148, 16, v86
	v_and_b32_e32 v149, 0xffff0000, v86
	v_lshlrev_b32_e32 v86, 16, v87
	v_and_b32_e32 v87, 0xffff0000, v87
	v_pk_add_f32 v[84:85], v[84:85], v[86:87]
	v_pk_add_f32 v[86:87], v[150:151], v[148:149]
	s_waitcnt vmcnt(16)
	v_lshlrev_b32_e32 v150, 16, v132
	v_and_b32_e32 v151, 0xffff0000, v132
	v_lshlrev_b32_e32 v132, 16, v133
	v_and_b32_e32 v133, 0xffff0000, v133
	s_waitcnt vmcnt(15)
	v_lshlrev_b32_e32 v152, 16, v130
	v_and_b32_e32 v153, 0xffff0000, v130
	v_lshlrev_b32_e32 v130, 16, v131
	v_and_b32_e32 v131, 0xffff0000, v131
	v_pk_add_f32 v[150:151], v[150:151], v[152:153]
	v_pk_add_f32 v[130:131], v[132:133], v[130:131]
	s_waitcnt vmcnt(14)
	v_lshlrev_b32_e32 v132, 16, v92
	v_and_b32_e32 v133, 0xffff0000, v92
	v_lshlrev_b32_e32 v92, 16, v93
	v_and_b32_e32 v93, 0xffff0000, v93
	v_pk_add_f32 v[92:93], v[130:131], v[92:93]
	v_pk_add_f32 v[130:131], v[150:151], v[132:133]
	s_waitcnt vmcnt(13)
	v_lshlrev_b32_e32 v132, 16, v94
	v_and_b32_e32 v133, 0xffff0000, v94
	v_lshlrev_b32_e32 v94, 16, v95
	v_and_b32_e32 v95, 0xffff0000, v95
	v_pk_add_f32 v[130:131], v[130:131], v[132:133]
	v_pk_add_f32 v[92:93], v[92:93], v[94:95]
	s_waitcnt vmcnt(12)
	v_lshlrev_b32_e32 v94, 16, v138
	v_and_b32_e32 v95, 0xffff0000, v138
	v_lshlrev_b32_e32 v132, 16, v139
	v_and_b32_e32 v133, 0xffff0000, v139
	v_pk_add_f32 v[92:93], v[92:93], v[132:133]
	v_pk_add_f32 v[94:95], v[130:131], v[94:95]
	s_waitcnt vmcnt(11)
	v_lshlrev_b32_e32 v130, 16, v134
	v_and_b32_e32 v131, 0xffff0000, v134
	v_lshlrev_b32_e32 v132, 16, v135
	v_and_b32_e32 v133, 0xffff0000, v135
	v_pk_add_f32 v[80:81], v[80:81], v[162:163]
	v_lshlrev_b32_e32 v162, 16, v172
	v_and_b32_e32 v163, 0xffff0000, v172
	v_pk_add_f32 v[94:95], v[94:95], v[130:131]
	v_pk_add_f32 v[92:93], v[92:93], v[132:133]
	s_waitcnt vmcnt(10)
; template <int MODE>
; __device__ __forceinline__ void norm_apply(f32x4 (&v)[8], bf16_t* xcopy, const f32x4 (&GG)[8], const f32x4 (&SS)[8], bf16_t* obf, float* of32, int lane, const float* slabrow = nullptr, const float* gate = nullptr) {
;     ...
;         for (int jh = 0; jh < 2; ++jh) { u32x2 p[4][8];
; #pragma unroll
;             for (int jj = 0; jj < 4; ++jj) { const int j = jh * 4 + jj; const u32x2* sp = (const u32x2*)((const bf16_t*)slabrow + (size_t)j * 8 * 65536) + lane;
; #pragma unroll
;                 for (int s = 0; s < 8; ++s) p[jj][s] = sp[(size_t)s * 16384]; }
;             __builtin_amdgcn_sched_barrier(0);
; #pragma unroll
;             for (int jj = 0; jj < 4; ++jj) { const int j = jh * 4 + jj; const f32x4 gt = ((const f32x4*)gate)[lane + 64 * j];
;                 f32x4 a = {bf_lo(p[jj][0].x), bf_hi(p[jj][0].x), bf_lo(p[jj][0].y), bf_hi(p[jj][0].y)};
; #pragma unroll
;                 for (int s = 1; s < 8; ++s) a += (f32x4){bf_lo(p[jj][s].x), bf_hi(p[jj][s].x), bf_lo(p[jj][s].y), bf_hi(p[jj][s].y)};
;                 v[j] += gt * a; }
	v_lshlrev_b32_e32 v130, 16, v136
	v_and_b32_e32 v131, 0xffff0000, v136
	v_lshlrev_b32_e32 v132, 16, v137
	v_and_b32_e32 v133, 0xffff0000, v137
	v_pk_add_f32 v[82:83], v[82:83], v[164:165]
	v_lshlrev_b32_e32 v164, 16, v173
	v_and_b32_e32 v165, 0xffff0000, v173
	v_pk_add_f32 v[162:163], v[80:81], v[162:163]
	v_lshlrev_b32_e32 v148, 16, v146
	v_and_b32_e32 v149, 0xffff0000, v146
	v_lshlrev_b32_e32 v146, 16, v147
	v_and_b32_e32 v147, 0xffff0000, v147
	v_pk_add_f32 v[92:93], v[92:93], v[132:133]
	v_pk_add_f32 v[94:95], v[94:95], v[130:131]
	s_waitcnt vmcnt(9)
	v_lshlrev_b32_e32 v130, 16, v140
	v_and_b32_e32 v131, 0xffff0000, v140
	v_lshlrev_b32_e32 v132, 16, v141
	v_and_b32_e32 v133, 0xffff0000, v141
	v_pk_add_f32 v[80:81], v[82:83], v[164:165]
	v_pk_add_f32 v[86:87], v[86:87], v[148:149]
	v_pk_add_f32 v[84:85], v[84:85], v[146:147]
	global_load_dwordx4 v[146:149], v[66:67], off offset:2048
	s_waitcnt vmcnt(1)
	v_pk_fma_f32 v[82:83], v[162:163], v[190:191], v[184:185]
	global_load_dwordx4 v[162:165], v[66:67], off offset:1024
	v_pk_add_f32 v[94:95], v[94:95], v[130:131]
	v_pk_add_f32 v[92:93], v[92:93], v[132:133]
	global_load_dwordx4 v[130:133], v[66:67], off offset:3072
	v_lshlrev_b32_e32 v134, 16, v122
	v_and_b32_e32 v135, 0xffff0000, v122
	v_lshlrev_b32_e32 v122, 16, v123
	v_and_b32_e32 v123, 0xffff0000, v123
	v_lshlrev_b32_e32 v136, 16, v118
	v_and_b32_e32 v137, 0xffff0000, v118
	v_lshlrev_b32_e32 v118, 16, v119
	v_and_b32_e32 v119, 0xffff0000, v119
	v_pk_add_f32 v[134:135], v[134:135], v[136:137]
	v_pk_add_f32 v[118:119], v[122:123], v[118:119]
	v_lshlrev_b32_e32 v122, 16, v114
	v_and_b32_e32 v123, 0xffff0000, v114
	v_lshlrev_b32_e32 v114, 16, v115
	v_and_b32_e32 v115, 0xffff0000, v115
	v_pk_add_f32 v[114:115], v[118:119], v[114:115]
	v_pk_add_f32 v[118:119], v[134:135], v[122:123]
	v_lshlrev_b32_e32 v122, 16, v100
	v_and_b32_e32 v123, 0xffff0000, v100
	v_lshlrev_b32_e32 v100, 16, v101
	v_and_b32_e32 v101, 0xffff0000, v101
	v_pk_add_f32 v[118:119], v[118:119], v[122:123]
	v_pk_add_f32 v[100:101], v[114:115], v[100:101]
	v_lshlrev_b32_e32 v114, 16, v124
	v_and_b32_e32 v115, 0xffff0000, v124
	v_lshlrev_b32_e32 v122, 16, v125
	v_and_b32_e32 v123, 0xffff0000, v125
	v_pk_add_f32 v[100:101], v[100:101], v[122:123]
	v_pk_add_f32 v[114:115], v[118:119], v[114:115]
	v_lshlrev_b32_e32 v118, 16, v116
	v_and_b32_e32 v119, 0xffff0000, v116
	v_lshlrev_b32_e32 v116, 16, v117
	v_and_b32_e32 v117, 0xffff0000, v117
	v_pk_add_f32 v[114:115], v[114:115], v[118:119]
	v_pk_add_f32 v[100:101], v[100:101], v[116:117]
	v_lshlrev_b32_e32 v116, 16, v102
	v_and_b32_e32 v117, 0xffff0000, v102
	v_lshlrev_b32_e32 v102, 16, v103
	v_and_b32_e32 v103, 0xffff0000, v103
	v_pk_add_f32 v[100:101], v[100:101], v[102:103]
	v_pk_add_f32 v[102:103], v[114:115], v[116:117]
	v_lshlrev_b32_e32 v114, 16, v126
	v_and_b32_e32 v115, 0xffff0000, v126
	v_lshlrev_b32_e32 v116, 16, v127
	v_and_b32_e32 v117, 0xffff0000, v127
	v_pk_add_f32 v[102:103], v[102:103], v[114:115]
	v_pk_add_f32 v[100:101], v[100:101], v[116:117]
	v_pk_fma_f32 v[80:81], v[80:81], v[192:193], v[188:189]
	s_waitcnt vmcnt(2)
	v_pk_fma_f32 v[92:93], v[92:93], v[148:149], v[144:145]
	v_pk_fma_f32 v[94:95], v[94:95], v[146:147], v[142:143]
	s_waitcnt vmcnt(1)
	v_pk_fma_f32 v[84:85], v[84:85], v[164:165], v[160:161]
	v_pk_fma_f32 v[86:87], v[86:87], v[162:163], v[158:159]
	s_waitcnt vmcnt(0)
	v_pk_fma_f32 v[100:101], v[132:133], v[100:101], v[128:129]
	v_pk_fma_f32 v[102:103], v[130:131], v[102:103], v[120:121]
	v_add_co_u32_e32 v114, vcc, s74, v104
	s_nop 1
	v_addc_co_u32_e32 v115, vcc, 0, v105, vcc
	v_add_co_u32_e32 v116, vcc, s68, v104
	s_nop 1
	v_addc_co_u32_e32 v117, vcc, 0, v105, vcc
	v_add_co_u32_e32 v118, vcc, s88, v104
	s_nop 1
	v_addc_co_u32_e32 v119, vcc, 0, v105, vcc
	v_add_co_u32_e32 v120, vcc, s93, v104
	s_nop 1
	v_addc_co_u32_e32 v121, vcc, 0, v105, vcc
	global_load_dwordx2 v[166:167], v[114:115], off
	global_load_dwordx2 v[168:169], v[116:117], off
	global_load_dwordx2 v[170:171], v[118:119], off
	global_load_dwordx2 v[172:173], v[120:121], off
	v_add_co_u32_e32 v114, vcc, s31, v104
	s_nop 1
	v_addc_co_u32_e32 v115, vcc, 0, v105, vcc
	v_add_co_u32_e32 v116, vcc, s89, v104
	s_nop 1
	v_addc_co_u32_e32 v117, vcc, 0, v105, vcc
	v_add_co_u32_e32 v118, vcc, s96, v104
	s_nop 1
	v_addc_co_u32_e32 v119, vcc, 0, v105, vcc
	v_add_co_u32_e32 v120, vcc, s34, v104
	s_nop 1
	v_addc_co_u32_e32 v121, vcc, 0, v105, vcc
	global_load_dwordx2 v[174:175], v[114:115], off
	global_load_dwordx2 v[176:177], v[116:117], off
	global_load_dwordx2 v[184:185], v[118:119], off
	global_load_dwordx2 v[188:189], v[120:121], off
	v_add_co_u32_e32 v114, vcc, s86, v104
	s_nop 1
	v_addc_co_u32_e32 v115, vcc, 0, v105, vcc
	v_add_co_u32_e32 v116, vcc, s72, v104
	s_nop 1
	v_addc_co_u32_e32 v117, vcc, 0, v105, vcc
	v_add_co_u32_e32 v118, vcc, s71, v104
	s_nop 1
	v_addc_co_u32_e32 v119, vcc, 0, v105, vcc
	v_add_co_u32_e32 v120, vcc, s77, v104
	s_nop 1
	v_addc_co_u32_e32 v121, vcc, 0, v105, vcc
	global_load_dwordx2 v[160:161], v[114:115], off
	global_load_dwordx2 v[158:159], v[116:117], off
	global_load_dwordx2 v[156:157], v[118:119], off
	global_load_dwordx2 v[152:153], v[120:121], off
	v_add_co_u32_e32 v114, vcc, s42, v104
	s_nop 1
	v_addc_co_u32_e32 v115, vcc, 0, v105, vcc
	v_add_co_u32_e32 v116, vcc, s79, v104
	s_nop 1
	v_addc_co_u32_e32 v117, vcc, 0, v105, vcc
	v_add_co_u32_e32 v118, vcc, s81, v104
	s_nop 1
	v_addc_co_u32_e32 v119, vcc, 0, v105, vcc
	v_add_co_u32_e32 v120, vcc, s75, v104
	s_nop 1
	v_addc_co_u32_e32 v121, vcc, 0, v105, vcc
	global_load_dwordx2 v[154:155], v[114:115], off
	global_load_dwordx2 v[150:151], v[116:117], off
; template <int MODE>
; __device__ __forceinline__ void norm_apply(f32x4 (&v)[8], bf16_t* xcopy, const f32x4 (&GG)[8], const f32x4 (&SS)[8], bf16_t* obf, float* of32, int lane, const float* slabrow = nullptr, const float* gate = nullptr) {
;     ...
;         for (int jh = 0; jh < 2; ++jh) { u32x2 p[4][8];
; #pragma unroll
;             for (int jj = 0; jj < 4; ++jj) { const int j = jh * 4 + jj; const u32x2* sp = (const u32x2*)((const bf16_t*)slabrow + (size_t)j * 8 * 65536) + lane;
; #pragma unroll
;                 for (int s = 0; s < 8; ++s) p[jj][s] = sp[(size_t)s * 16384]; }
;             __builtin_amdgcn_sched_barrier(0);
; #pragma unroll
;             for (int jj = 0; jj < 4; ++jj) { const int j = jh * 4 + jj; const f32x4 gt = ((const f32x4*)gate)[lane + 64 * j];
;                 f32x4 a = {bf_lo(p[jj][0].x), bf_hi(p[jj][0].x), bf_lo(p[jj][0].y), bf_hi(p[jj][0].y)};
; #pragma unroll
;                 for (int s = 1; s < 8; ++s) a += (f32x4){bf_lo(p[jj][s].x), bf_hi(p[jj][s].x), bf_lo(p[jj][s].y), bf_hi(p[jj][s].y)};
;                 v[j] += gt * a; }
	global_load_dwordx2 v[148:149], v[118:119], off
	global_load_dwordx2 v[146:147], v[120:121], off
	v_add_co_u32_e32 v114, vcc, s35, v104
	s_nop 1
	v_addc_co_u32_e32 v115, vcc, 0, v105, vcc
	v_add_co_u32_e32 v116, vcc, s95, v104
	s_nop 1
	v_addc_co_u32_e32 v117, vcc, 0, v105, vcc
	v_add_co_u32_e32 v118, vcc, s87, v104
	s_nop 1
	v_addc_co_u32_e32 v119, vcc, 0, v105, vcc
	v_add_co_u32_e32 v120, vcc, s40, v104
	s_nop 1
	v_addc_co_u32_e32 v121, vcc, 0, v105, vcc
	global_load_dwordx2 v[144:145], v[114:115], off
	global_load_dwordx2 v[142:143], v[116:117], off
	global_load_dwordx2 v[136:137], v[118:119], off
	global_load_dwordx2 v[132:133], v[120:121], off
	v_add_co_u32_e32 v114, vcc, s97, v104
	s_nop 1
	v_addc_co_u32_e32 v115, vcc, 0, v105, vcc
	v_add_co_u32_e32 v116, vcc, s73, v104
	s_nop 1
	v_addc_co_u32_e32 v117, vcc, 0, v105, vcc
	v_add_co_u32_e32 v118, vcc, s44, v104
	s_nop 1
	v_addc_co_u32_e32 v119, vcc, 0, v105, vcc
	v_add_co_u32_e32 v120, vcc, s45, v104
	s_nop 1
	v_addc_co_u32_e32 v121, vcc, 0, v105, vcc
	global_load_dwordx2 v[140:141], v[114:115], off
	global_load_dwordx2 v[138:139], v[116:117], off
	global_load_dwordx2 v[134:135], v[118:119], off
	global_load_dwordx2 v[130:131], v[120:121], off
	v_add_co_u32_e32 v114, vcc, s46, v104
	s_nop 1
	v_addc_co_u32_e32 v115, vcc, 0, v105, vcc
	v_add_co_u32_e32 v116, vcc, s47, v104
	s_nop 1
	v_addc_co_u32_e32 v117, vcc, 0, v105, vcc
	v_add_co_u32_e32 v118, vcc, s92, v104
	s_nop 1
	v_addc_co_u32_e32 v119, vcc, 0, v105, vcc
	v_add_co_u32_e32 v120, vcc, s1, v104
	s_nop 1
	v_addc_co_u32_e32 v121, vcc, 0, v105, vcc
	global_load_dwordx2 v[128:129], v[114:115], off
	global_load_dwordx2 v[126:127], v[116:117], off
	global_load_dwordx2 v[122:123], v[118:119], off
	s_nop 0
	global_load_dwordx2 v[120:121], v[120:121], off
	v_add_co_u32_e32 v114, vcc, s41, v104
	s_nop 1
	v_addc_co_u32_e32 v115, vcc, 0, v105, vcc
	v_add_co_u32_e32 v116, vcc, s36, v104
	s_nop 1
	v_addc_co_u32_e32 v117, vcc, 0, v105, vcc
	v_add_co_u32_e32 v162, vcc, s50, v104
	s_nop 1
	v_addc_co_u32_e32 v163, vcc, 0, v105, vcc
	v_add_co_u32_e32 v104, vcc, s63, v104
	s_nop 1
	v_addc_co_u32_e32 v105, vcc, 0, v105, vcc
	global_load_dwordx2 v[124:125], v[114:115], off
	global_load_dwordx2 v[118:119], v[116:117], off
	s_nop 0
	global_load_dwordx2 v[116:117], v[162:163], off
	global_load_dwordx2 v[114:115], v[104:105], off
	s_nop 0
	global_load_dwordx4 v[162:165], v[68:69], off
	s_waitcnt vmcnt(32)
	v_lshlrev_b32_e32 v104, 16, v166
	v_and_b32_e32 v105, 0xffff0000, v166
	v_lshlrev_b32_e32 v166, 16, v167
	v_and_b32_e32 v167, 0xffff0000, v167
	s_waitcnt vmcnt(31)
	v_lshlrev_b32_e32 v190, 16, v168
	v_and_b32_e32 v191, 0xffff0000, v168
	v_lshlrev_b32_e32 v168, 16, v169
	v_and_b32_e32 v169, 0xffff0000, v169
	v_pk_add_f32 v[104:105], v[104:105], v[190:191]
	v_pk_add_f32 v[166:167], v[166:167], v[168:169]
	s_waitcnt vmcnt(30)
	v_lshlrev_b32_e32 v168, 16, v170
	v_and_b32_e32 v169, 0xffff0000, v170
	v_lshlrev_b32_e32 v170, 16, v171
	v_and_b32_e32 v171, 0xffff0000, v171
	v_pk_add_f32 v[166:167], v[166:167], v[170:171]
	v_pk_add_f32 v[104:105], v[104:105], v[168:169]
	s_waitcnt vmcnt(29)
	v_lshlrev_b32_e32 v168, 16, v172
	v_and_b32_e32 v169, 0xffff0000, v172
	v_lshlrev_b32_e32 v170, 16, v173
	v_and_b32_e32 v171, 0xffff0000, v173
	v_pk_add_f32 v[104:105], v[104:105], v[168:169]
	v_pk_add_f32 v[166:167], v[166:167], v[170:171]
	s_waitcnt vmcnt(28)
	v_lshlrev_b32_e32 v168, 16, v174
	v_and_b32_e32 v169, 0xffff0000, v174
	v_lshlrev_b32_e32 v170, 16, v175
	v_and_b32_e32 v171, 0xffff0000, v175
	v_pk_add_f32 v[166:167], v[166:167], v[170:171]
	v_pk_add_f32 v[104:105], v[104:105], v[168:169]
	s_waitcnt vmcnt(27)
	v_lshlrev_b32_e32 v168, 16, v176
	v_and_b32_e32 v169, 0xffff0000, v176
	v_lshlrev_b32_e32 v170, 16, v177
	v_and_b32_e32 v171, 0xffff0000, v177
	v_pk_add_f32 v[104:105], v[104:105], v[168:169]
	v_pk_add_f32 v[166:167], v[166:167], v[170:171]
	s_waitcnt vmcnt(26)
	v_lshlrev_b32_e32 v168, 16, v184
	v_and_b32_e32 v169, 0xffff0000, v184
	v_lshlrev_b32_e32 v170, 16, v185
	v_and_b32_e32 v171, 0xffff0000, v185
	v_pk_add_f32 v[166:167], v[166:167], v[170:171]
	v_pk_add_f32 v[104:105], v[104:105], v[168:169]
	s_waitcnt vmcnt(25)
	v_lshlrev_b32_e32 v168, 16, v188
	v_and_b32_e32 v169, 0xffff0000, v188
	v_lshlrev_b32_e32 v170, 16, v189
	v_and_b32_e32 v171, 0xffff0000, v189
	v_pk_add_f32 v[168:169], v[104:105], v[168:169]
	v_pk_add_f32 v[104:105], v[166:167], v[170:171]
	s_waitcnt vmcnt(23)
	v_lshlrev_b32_e32 v166, 16, v158
	v_and_b32_e32 v167, 0xffff0000, v158
	v_lshlrev_b32_e32 v158, 16, v159
	v_and_b32_e32 v159, 0xffff0000, v159
	s_waitcnt vmcnt(0)
	v_pk_fma_f32 v[104:105], v[104:105], v[164:165], v[112:113]
	v_pk_fma_f32 v[106:107], v[168:169], v[162:163], v[106:107]
	global_load_dwordx4 v[162:165], v[70:71], off
	v_lshlrev_b32_e32 v112, 16, v160
	v_and_b32_e32 v113, 0xffff0000, v160
	v_lshlrev_b32_e32 v160, 16, v161
	v_and_b32_e32 v161, 0xffff0000, v161
	v_pk_add_f32 v[158:159], v[160:161], v[158:159]
	v_lshlrev_b32_e32 v160, 16, v156
	v_and_b32_e32 v161, 0xffff0000, v156
	v_lshlrev_b32_e32 v156, 16, v157
	v_and_b32_e32 v157, 0xffff0000, v157
	v_pk_add_f32 v[156:157], v[158:159], v[156:157]
	v_lshlrev_b32_e32 v158, 16, v152
	v_and_b32_e32 v159, 0xffff0000, v152
	v_lshlrev_b32_e32 v152, 16, v153
	v_and_b32_e32 v153, 0xffff0000, v153
	v_pk_add_f32 v[152:153], v[156:157], v[152:153]
	v_lshlrev_b32_e32 v156, 16, v154
	v_and_b32_e32 v157, 0xffff0000, v154
	v_lshlrev_b32_e32 v154, 16, v155
	v_and_b32_e32 v155, 0xffff0000, v155
	v_pk_add_f32 v[152:153], v[152:153], v[154:155]
	v_lshlrev_b32_e32 v154, 16, v150
	v_and_b32_e32 v155, 0xffff0000, v150
	v_lshlrev_b32_e32 v150, 16, v151
	v_and_b32_e32 v151, 0xffff0000, v151
	v_pk_add_f32 v[150:151], v[152:153], v[150:151]
	v_lshlrev_b32_e32 v152, 16, v148
	v_and_b32_e32 v153, 0xffff0000, v148
	v_lshlrev_b32_e32 v148, 16, v149
	v_and_b32_e32 v149, 0xffff0000, v149
	v_pk_add_f32 v[148:149], v[150:151], v[148:149]
	v_lshlrev_b32_e32 v150, 16, v146
	v_and_b32_e32 v151, 0xffff0000, v146
	v_lshlrev_b32_e32 v146, 16, v147
	v_and_b32_e32 v147, 0xffff0000, v147
	v_pk_add_f32 v[146:147], v[148:149], v[146:147]
	v_pk_add_f32 v[112:113], v[112:113], v[166:167]
	s_waitcnt vmcnt(0)
; template <int MODE>
; __device__ __forceinline__ void norm_apply(f32x4 (&v)[8], bf16_t* xcopy, const f32x4 (&GG)[8], const f32x4 (&SS)[8], bf16_t* obf, float* of32, int lane, const float* slabrow = nullptr, const float* gate = nullptr) {
;     ...
;             for (int jj = 0; jj < 4; ++jj) { const int j = jh * 4 + jj; const f32x4 gt = ((const f32x4*)gate)[lane + 64 * j];
;                 f32x4 a = {bf_lo(p[jj][0].x), bf_hi(p[jj][0].x), bf_lo(p[jj][0].y), bf_hi(p[jj][0].y)};
; #pragma unroll
;                 for (int s = 1; s < 8; ++s) a += (f32x4){bf_lo(p[jj][s].x), bf_hi(p[jj][s].x), bf_lo(p[jj][s].y), bf_hi(p[jj][s].y)};
;                 v[j] += gt * a; }
	v_pk_fma_f32 v[110:111], v[146:147], v[164:165], v[110:111]
	global_load_dwordx4 v[146:149], v[72:73], off
	v_pk_add_f32 v[112:113], v[112:113], v[160:161]
	s_nop 0
	v_pk_add_f32 v[112:113], v[112:113], v[158:159]
	s_nop 0
	v_pk_add_f32 v[112:113], v[112:113], v[156:157]
	s_nop 0
	v_pk_add_f32 v[112:113], v[112:113], v[154:155]
	s_nop 0
	v_pk_add_f32 v[112:113], v[112:113], v[152:153]
	s_nop 0
	v_pk_add_f32 v[112:113], v[112:113], v[150:151]
	v_lshlrev_b32_e32 v150, 16, v142
	v_pk_fma_f32 v[108:109], v[112:113], v[162:163], v[108:109]
	v_lshlrev_b32_e32 v112, 16, v144
	v_and_b32_e32 v113, 0xffff0000, v144
	v_lshlrev_b32_e32 v144, 16, v145
	v_and_b32_e32 v145, 0xffff0000, v145
	v_and_b32_e32 v151, 0xffff0000, v142
	v_lshlrev_b32_e32 v142, 16, v143
	v_and_b32_e32 v143, 0xffff0000, v143
	v_pk_add_f32 v[112:113], v[112:113], v[150:151]
	v_pk_add_f32 v[142:143], v[144:145], v[142:143]
	v_lshlrev_b32_e32 v144, 16, v136
	v_and_b32_e32 v145, 0xffff0000, v136
	v_lshlrev_b32_e32 v136, 16, v137
	v_and_b32_e32 v137, 0xffff0000, v137
	v_pk_add_f32 v[136:137], v[142:143], v[136:137]
	v_pk_add_f32 v[112:113], v[112:113], v[144:145]
	v_lshlrev_b32_e32 v142, 16, v132
	v_and_b32_e32 v143, 0xffff0000, v132
	v_lshlrev_b32_e32 v132, 16, v133
	v_and_b32_e32 v133, 0xffff0000, v133
	v_pk_add_f32 v[112:113], v[112:113], v[142:143]
	v_pk_add_f32 v[132:133], v[136:137], v[132:133]
	v_lshlrev_b32_e32 v136, 16, v140
	v_and_b32_e32 v137, 0xffff0000, v140
	v_lshlrev_b32_e32 v140, 16, v141
	v_and_b32_e32 v141, 0xffff0000, v141
	v_pk_add_f32 v[132:133], v[132:133], v[140:141]
	v_pk_add_f32 v[112:113], v[112:113], v[136:137]
	v_lshlrev_b32_e32 v136, 16, v138
	v_and_b32_e32 v137, 0xffff0000, v138
	v_lshlrev_b32_e32 v138, 16, v139
	v_and_b32_e32 v139, 0xffff0000, v139
	v_pk_add_f32 v[112:113], v[112:113], v[136:137]
	v_pk_add_f32 v[132:133], v[132:133], v[138:139]
	v_lshlrev_b32_e32 v136, 16, v134
	v_and_b32_e32 v137, 0xffff0000, v134
	v_lshlrev_b32_e32 v134, 16, v135
	v_and_b32_e32 v135, 0xffff0000, v135
	v_pk_add_f32 v[132:133], v[132:133], v[134:135]
	v_lshlrev_b32_e32 v134, 16, v130
	v_and_b32_e32 v135, 0xffff0000, v130
	v_lshlrev_b32_e32 v130, 16, v131
	v_and_b32_e32 v131, 0xffff0000, v131
	v_pk_add_f32 v[130:131], v[132:133], v[130:131]
	v_pk_add_f32 v[112:113], v[112:113], v[136:137]
	s_waitcnt vmcnt(0)
	v_pk_fma_f32 v[98:99], v[130:131], v[148:149], v[98:99]
	global_load_dwordx4 v[130:133], v[74:75], off
	v_pk_add_f32 v[112:113], v[112:113], v[134:135]
	v_lshlrev_b32_e32 v134, 16, v126
	v_pk_fma_f32 v[96:97], v[112:113], v[146:147], v[96:97]
	v_lshlrev_b32_e32 v112, 16, v128
	v_and_b32_e32 v113, 0xffff0000, v128
	v_lshlrev_b32_e32 v128, 16, v129
	v_and_b32_e32 v129, 0xffff0000, v129
	v_and_b32_e32 v135, 0xffff0000, v126
	v_lshlrev_b32_e32 v126, 16, v127
	v_and_b32_e32 v127, 0xffff0000, v127
	v_pk_add_f32 v[112:113], v[112:113], v[134:135]
	v_pk_add_f32 v[126:127], v[128:129], v[126:127]
	v_lshlrev_b32_e32 v128, 16, v122
	v_and_b32_e32 v129, 0xffff0000, v122
	v_lshlrev_b32_e32 v122, 16, v123
	v_and_b32_e32 v123, 0xffff0000, v123
	v_pk_add_f32 v[122:123], v[126:127], v[122:123]
	v_pk_add_f32 v[112:113], v[112:113], v[128:129]
	v_lshlrev_b32_e32 v126, 16, v120
	v_and_b32_e32 v127, 0xffff0000, v120
	v_lshlrev_b32_e32 v120, 16, v121
	v_and_b32_e32 v121, 0xffff0000, v121
	v_pk_add_f32 v[112:113], v[112:113], v[126:127]
	v_pk_add_f32 v[120:121], v[122:123], v[120:121]
	v_lshlrev_b32_e32 v122, 16, v124
	v_and_b32_e32 v123, 0xffff0000, v124
	v_lshlrev_b32_e32 v124, 16, v125
	v_and_b32_e32 v125, 0xffff0000, v125
	v_pk_add_f32 v[120:121], v[120:121], v[124:125]
	v_pk_add_f32 v[112:113], v[112:113], v[122:123]
	v_lshlrev_b32_e32 v122, 16, v118
	v_and_b32_e32 v123, 0xffff0000, v118
	v_lshlrev_b32_e32 v118, 16, v119
	v_and_b32_e32 v119, 0xffff0000, v119
	v_pk_add_f32 v[112:113], v[112:113], v[122:123]
	v_pk_add_f32 v[118:119], v[120:121], v[118:119]
	v_lshlrev_b32_e32 v120, 16, v116
	v_and_b32_e32 v121, 0xffff0000, v116
	v_lshlrev_b32_e32 v116, 16, v117
	v_and_b32_e32 v117, 0xffff0000, v117
	v_pk_add_f32 v[116:117], v[118:119], v[116:117]
	v_pk_add_f32 v[112:113], v[112:113], v[120:121]
	v_lshlrev_b32_e32 v118, 16, v114
	v_and_b32_e32 v119, 0xffff0000, v114
	v_lshlrev_b32_e32 v114, 16, v115
	v_and_b32_e32 v115, 0xffff0000, v115
	v_pk_add_f32 v[112:113], v[112:113], v[118:119]
	v_pk_add_f32 v[114:115], v[116:117], v[114:115]
	s_waitcnt vmcnt(0)
; __device__ __forceinline__ unsigned pk2(float lo, float hi) { return f2bf(lo) | (f2bf(hi) << 16); }
; __device__ __forceinline__ float wave_sum(float v) {
; #pragma unroll
;     for (int o = 1; o < 64; o <<= 1) v += __shfl_xor(v, o);
;     return v;
; template <int MODE>
; __device__ __forceinline__ void norm_apply(f32x4 (&v)[8], bf16_t* xcopy, const f32x4 (&GG)[8], const f32x4 (&SS)[8], bf16_t* obf, float* of32, int lane, const float* slabrow = nullptr, const float* gate = nullptr) {
;     ...
; #pragma unroll
;     for (int j = 0; j < 8; ++j) ss += (v[j].x * v[j].x + v[j].y * v[j].y) + (v[j].z * v[j].z + v[j].w * v[j].w);
;     const float rstd = rsqrtf(wave_sum(ss) * (1.f / D) + 1e-6f);
;     if (xcopy) {
; #pragma unroll
;         for (int j = 0; j < 8; ++j) { u32x2 w; w.x = pk2(v[j].x, v[j].y); w.y = pk2(v[j].z, v[j].w); ((u32x2*)xcopy)[lane + 64 * j] = w; } }
	v_pk_fma_f32 v[88:89], v[130:131], v[112:113], v[88:89]
	v_pk_fma_f32 v[90:91], v[132:133], v[114:115], v[90:91]
	v_mov_b32_e32 v114, v83
	v_mov_b32_e32 v115, v87
	v_mov_b32_e32 v112, v82
	v_mov_b32_e32 v113, v86
	v_pk_mul_f32 v[114:115], v[114:115], v[114:115]
	v_mov_b32_e32 v116, v81
	v_mov_b32_e32 v117, v85
	v_pk_fma_f32 v[112:113], v[112:113], v[112:113], v[114:115]
	v_mov_b32_e32 v114, v80
	v_mov_b32_e32 v115, v84
	v_pk_mul_f32 v[116:117], v[116:117], v[116:117]
	s_add_i32 s14, s14, s84
	v_pk_fma_f32 v[114:115], v[114:115], v[114:115], v[116:117]
	v_pk_mul_f32 v[116:117], v[94:95], v[94:95]
	v_pk_add_f32 v[112:113], v[112:113], v[114:115]
	v_pk_mul_f32 v[114:115], v[92:93], v[92:93]
	v_pk_add_f32 v[112:113], v[112:113], v[112:113] op_sel:[0,1] op_sel_hi:[1,0]
	v_pk_mov_b32 v[118:119], v[116:117], v[114:115] op_sel:[1,0]
	v_mov_b32_e32 v117, v115
	v_pk_add_f32 v[114:115], v[118:119], v[116:117]
	v_mul_f32_e32 v116, v106, v106
	v_mul_f32_e32 v117, v107, v107
	v_pk_add_f32 v[114:115], v[114:115], v[114:115] op_sel:[0,1] op_sel_hi:[1,0]
	v_mov_b32_e32 v113, v116
	v_mov_b32_e32 v115, v117
	v_pk_add_f32 v[112:113], v[112:113], v[114:115]
	v_mul_f32_e32 v114, v103, v103
	v_mul_f32_e32 v116, v101, v101
	v_mul_f32_e32 v118, v104, v104
	v_mul_f32_e32 v119, v105, v105
	v_pk_fma_f32 v[114:115], v[102:103], v[102:103], v[114:115] op_sel_hi:[1,1,0]
	v_pk_fma_f32 v[116:117], v[100:101], v[100:101], v[116:117] op_sel_hi:[1,1,0]
	v_mov_b32_e32 v115, v118
	v_mov_b32_e32 v117, v119
	v_pk_add_f32 v[114:115], v[114:115], v[116:117]
	v_pk_mul_f32 v[116:117], v[108:109], v[108:109]
	v_pk_add_f32 v[112:113], v[112:113], v[114:115]
	v_pk_mul_f32 v[114:115], v[110:111], v[110:111]
	v_pk_add_f32 v[112:113], v[112:113], v[112:113] op_sel:[0,1] op_sel_hi:[1,0]
	v_pk_mov_b32 v[118:119], v[116:117], v[114:115] op_sel:[1,0]
	v_mov_b32_e32 v117, v115
	v_pk_add_f32 v[114:115], v[118:119], v[116:117]
	v_mul_f32_e32 v116, v88, v88
	v_mul_f32_e32 v117, v89, v89
	v_pk_add_f32 v[114:115], v[114:115], v[114:115] op_sel:[0,1] op_sel_hi:[1,0]
	v_mov_b32_e32 v113, v116
	v_mov_b32_e32 v115, v117
	v_pk_add_f32 v[112:113], v[112:113], v[114:115]
	v_mul_f32_e32 v114, v97, v97
	v_mul_f32_e32 v116, v99, v99
	v_mul_f32_e32 v118, v90, v90
	v_mul_f32_e32 v119, v91, v91
	v_pk_fma_f32 v[114:115], v[96:97], v[96:97], v[114:115] op_sel_hi:[1,1,0]
	v_pk_fma_f32 v[116:117], v[98:99], v[98:99], v[116:117] op_sel_hi:[1,1,0]
	v_mov_b32_e32 v115, v118
	v_mov_b32_e32 v117, v119
	v_pk_add_f32 v[114:115], v[114:115], v[116:117]
	v_bfe_u32 v116, v81, 16, 1
	v_pk_add_f32 v[112:113], v[112:113], v[114:115]
	v_add3_u32 v116, v81, v116, s8
	v_add_f32_e32 v112, v112, v113
	ds_bpermute_b32 v113, v178, v112
	s_add_i32 s4, s14, 0x2000
	s_add_i32 s10, s10, s67
	s_cmpk_lt_i32 s4, 0x2400
	s_waitcnt lgkmcnt(0)
	v_add_f32_e32 v112, v112, v113
	ds_bpermute_b32 v113, v179, v112
	s_waitcnt lgkmcnt(0)
	v_add_f32_e32 v112, v112, v113
	ds_bpermute_b32 v113, v180, v112
	s_waitcnt lgkmcnt(0)
	v_add_f32_e32 v112, v112, v113
	ds_bpermute_b32 v113, v181, v112
	s_waitcnt lgkmcnt(0)
	v_add_f32_e32 v112, v112, v113
	ds_bpermute_b32 v113, v182, v112
	s_waitcnt lgkmcnt(0)
	v_add_f32_e32 v114, v112, v113
	v_bfe_u32 v112, v82, 16, 1
	v_add3_u32 v112, v82, v112, s8
	v_bfe_u32 v113, v83, 16, 1
	v_lshrrev_b32_e32 v112, 16, v112
	v_add3_u32 v113, v83, v113, s8
	v_and_or_b32 v112, v113, s58, v112
	v_bfe_u32 v113, v80, 16, 1
	v_add3_u32 v113, v80, v113, s8
	v_lshrrev_b32_e32 v113, 16, v113
	v_and_or_b32 v113, v116, s58, v113
	global_store_dwordx2 v[78:79], v[112:113], off offset:-3584
	v_bfe_u32 v112, v86, 16, 1
	v_add3_u32 v112, v86, v112, s8
	v_bfe_u32 v113, v87, 16, 1
	v_lshrrev_b32_e32 v112, 16, v112
	v_add3_u32 v113, v87, v113, s8
	v_and_or_b32 v112, v113, s58, v112
	v_bfe_u32 v113, v84, 16, 1
	v_add3_u32 v113, v84, v113, s8
	v_bfe_u32 v116, v85, 16, 1
	v_lshrrev_b32_e32 v113, 16, v113
	v_add3_u32 v116, v85, v116, s8
	v_and_or_b32 v113, v116, s58, v113
	global_store_dwordx2 v[78:79], v[112:113], off offset:-3072
	v_bfe_u32 v112, v94, 16, 1
	v_add3_u32 v112, v94, v112, s8
	v_bfe_u32 v113, v95, 16, 1
	v_lshrrev_b32_e32 v112, 16, v112
	v_add3_u32 v113, v95, v113, s8
	v_and_or_b32 v112, v113, s58, v112
	v_bfe_u32 v113, v92, 16, 1
	v_add3_u32 v113, v92, v113, s8
	v_bfe_u32 v116, v93, 16, 1
	v_lshrrev_b32_e32 v113, 16, v113
	v_add3_u32 v116, v93, v116, s8
	v_and_or_b32 v113, v116, s58, v113
	global_store_dwordx2 v[78:79], v[112:113], off offset:-2560
	v_bfe_u32 v112, v102, 16, 1
	v_add3_u32 v112, v102, v112, s8
	v_bfe_u32 v113, v103, 16, 1
	v_lshrrev_b32_e32 v112, 16, v112
	v_add3_u32 v113, v103, v113, s8
	v_and_or_b32 v112, v113, s58, v112
	v_bfe_u32 v113, v100, 16, 1
	v_add3_u32 v113, v100, v113, s8
	v_bfe_u32 v116, v101, 16, 1
	v_lshrrev_b32_e32 v113, 16, v113
	v_add3_u32 v116, v101, v116, s8
	v_and_or_b32 v113, v116, s58, v113
	global_store_dwordx2 v[78:79], v[112:113], off offset:-2048
	v_bfe_u32 v112, v106, 16, 1
	v_add3_u32 v112, v106, v112, s8
	v_bfe_u32 v113, v107, 16, 1
	v_lshrrev_b32_e32 v112, 16, v112
	v_add3_u32 v113, v107, v113, s8
	v_and_or_b32 v112, v113, s58, v112
	v_bfe_u32 v113, v104, 16, 1
	v_add3_u32 v113, v104, v113, s8
	v_bfe_u32 v116, v105, 16, 1
	v_lshrrev_b32_e32 v113, 16, v113
	v_add3_u32 v116, v105, v116, s8
	v_and_or_b32 v113, v116, s58, v113
	global_store_dwordx2 v[78:79], v[112:113], off offset:-1536
	v_bfe_u32 v112, v108, 16, 1
	v_add3_u32 v112, v108, v112, s8
	v_bfe_u32 v113, v109, 16, 1
	v_lshrrev_b32_e32 v112, 16, v112
	v_add3_u32 v113, v109, v113, s8
	v_and_or_b32 v112, v113, s58, v112
	v_bfe_u32 v113, v110, 16, 1
	v_add3_u32 v113, v110, v113, s8
	v_bfe_u32 v116, v111, 16, 1
	v_lshrrev_b32_e32 v113, 16, v113
	v_add3_u32 v116, v111, v116, s8
	v_and_or_b32 v113, v116, s58, v113
	global_store_dwordx2 v[78:79], v[112:113], off offset:-1024
	v_bfe_u32 v112, v96, 16, 1
	v_add3_u32 v112, v96, v112, s8
	v_bfe_u32 v113, v97, 16, 1
	v_lshrrev_b32_e32 v112, 16, v112
	v_add3_u32 v113, v97, v113, s8
	v_and_or_b32 v112, v113, s58, v112
	v_bfe_u32 v113, v98, 16, 1
	v_add3_u32 v113, v98, v113, s8
	v_bfe_u32 v116, v99, 16, 1
	v_lshrrev_b32_e32 v113, 16, v113
	v_add3_u32 v116, v99, v116, s8
	v_and_or_b32 v113, v116, s58, v113
	global_store_dwordx2 v[78:79], v[112:113], off offset:-512
	v_bfe_u32 v112, v88, 16, 1
	v_add3_u32 v112, v88, v112, s8
	v_bfe_u32 v113, v89, 16, 1
	ds_bpermute_b32 v115, v183, v114
	v_lshrrev_b32_e32 v112, 16, v112
	v_add3_u32 v113, v89, v113, s8
	v_and_or_b32 v112, v113, s58, v112
	v_bfe_u32 v113, v90, 16, 1
	v_add3_u32 v113, v90, v113, s8
	v_bfe_u32 v116, v91, 16, 1
	v_lshrrev_b32_e32 v113, 16, v113
	v_add3_u32 v116, v91, v116, s8
	v_and_or_b32 v113, v116, s58, v113
	global_store_dwordx2 v[78:79], v[112:113], off
	s_waitcnt lgkmcnt(0)
; __device__ __forceinline__ unsigned pk2(float lo, float hi) { return f2bf(lo) | (f2bf(hi) << 16); }
; template <int MODE>
; __device__ __forceinline__ void norm_apply(f32x4 (&v)[8], bf16_t* xcopy, const f32x4 (&GG)[8], const f32x4 (&SS)[8], bf16_t* obf, float* of32, int lane, const float* slabrow = nullptr, const float* gate = nullptr) {
;     ...
;     const float rstd = rsqrtf(wave_sum(ss) * (1.f / D) + 1e-6f);
;     if (xcopy) {
; #pragma unroll
;         for (int j = 0; j < 8; ++j) { u32x2 w; w.x = pk2(v[j].x, v[j].y); w.y = pk2(v[j].z, v[j].w); ((u32x2*)xcopy)[lane + 64 * j] = w; } }
; #pragma unroll
;     for (int j = 0; j < 8; ++j) { const int c4 = lane + 64 * j;
;         f32x4 h = v[j] * rstd * GG[j];
;         if (MODE == 0) { h = h + SS[j]; u32x2 w; w.x = pk2(h.x, h.y); w.y = pk2(h.z, h.w); ((u32x2*)obf)[c4] = w; }
;         else ((f32x4*)of32)[c4] = h; }
	v_add_f32_e32 v78, v114, v115
	v_fmamk_f32 v78, v78, 0x3a000000, v238
	v_cmp_gt_f32_e32 vcc, s56, v78
	v_mul_f32_e32 v79, 0x4b800000, v78
	s_nop 0
	v_cndmask_b32_e32 v78, v78, v79, vcc
	v_rsq_f32_e32 v78, v78
	s_nop 0
	v_mul_f32_e32 v79, 0x45800000, v78
	v_cndmask_b32_e32 v78, v78, v79, vcc
	v_pk_mul_f32 v[82:83], v[82:83], v[78:79] op_sel_hi:[1,0]
	v_pk_mul_f32 v[80:81], v[80:81], v[78:79] op_sel_hi:[1,0]
	v_pk_fma_f32 v[82:83], v[36:37], v[82:83], v[2:3]
	v_pk_fma_f32 v[80:81], v[34:35], v[80:81], v[4:5]
	v_bfe_u32 v79, v82, 16, 1
	v_add3_u32 v79, v82, v79, s8
	v_bfe_u32 v82, v83, 16, 1
	v_lshrrev_b32_e32 v79, 16, v79
	v_add3_u32 v82, v83, v82, s8
	v_and_or_b32 v82, v82, s58, v79
	v_bfe_u32 v79, v80, 16, 1
	v_add3_u32 v79, v80, v79, s8
	v_bfe_u32 v80, v81, 16, 1
	v_lshrrev_b32_e32 v79, 16, v79
	v_add3_u32 v80, v81, v80, s8
	v_and_or_b32 v83, v80, s58, v79
	v_pk_mul_f32 v[80:81], v[86:87], v[78:79] op_sel_hi:[1,0]
	global_store_dwordx2 v[76:77], v[82:83], off offset:-3584
	v_pk_fma_f32 v[80:81], v[40:41], v[80:81], v[6:7]
	v_pk_mul_f32 v[82:83], v[84:85], v[78:79] op_sel_hi:[1,0]
	v_bfe_u32 v79, v80, 16, 1
	v_add3_u32 v79, v80, v79, s8
	v_bfe_u32 v80, v81, 16, 1
	v_pk_fma_f32 v[82:83], v[38:39], v[82:83], v[8:9]
	v_lshrrev_b32_e32 v79, 16, v79
	v_add3_u32 v80, v81, v80, s8
	v_and_or_b32 v80, v80, s58, v79
	v_bfe_u32 v79, v82, 16, 1
	v_add3_u32 v79, v82, v79, s8
	v_bfe_u32 v81, v83, 16, 1
	v_lshrrev_b32_e32 v79, 16, v79
	v_add3_u32 v81, v83, v81, s8
	v_and_or_b32 v81, v81, s58, v79
	global_store_dwordx2 v[76:77], v[80:81], off offset:-3072
	v_pk_mul_f32 v[80:81], v[94:95], v[78:79] op_sel_hi:[1,0]
	v_pk_mul_f32 v[82:83], v[92:93], v[78:79] op_sel_hi:[1,0]
	v_pk_fma_f32 v[80:81], v[44:45], v[80:81], v[10:11]
	v_pk_fma_f32 v[82:83], v[42:43], v[82:83], v[12:13]
	v_bfe_u32 v79, v80, 16, 1
	v_add3_u32 v79, v80, v79, s8
	v_bfe_u32 v80, v81, 16, 1
	v_lshrrev_b32_e32 v79, 16, v79
	v_add3_u32 v80, v81, v80, s8
	v_and_or_b32 v80, v80, s58, v79
	v_bfe_u32 v79, v82, 16, 1
	v_add3_u32 v79, v82, v79, s8
	v_bfe_u32 v81, v83, 16, 1
	v_lshrrev_b32_e32 v79, 16, v79
	v_add3_u32 v81, v83, v81, s8
	v_and_or_b32 v81, v81, s58, v79
	global_store_dwordx2 v[76:77], v[80:81], off offset:-2560
	v_pk_mul_f32 v[80:81], v[102:103], v[78:79] op_sel_hi:[1,0]
	v_pk_mul_f32 v[82:83], v[100:101], v[78:79] op_sel_hi:[1,0]
	v_pk_fma_f32 v[80:81], v[48:49], v[80:81], v[14:15]
	v_pk_fma_f32 v[82:83], v[46:47], v[82:83], v[16:17]
	v_bfe_u32 v79, v80, 16, 1
	v_add3_u32 v79, v80, v79, s8
	v_bfe_u32 v80, v81, 16, 1
	v_lshrrev_b32_e32 v79, 16, v79
	v_add3_u32 v80, v81, v80, s8
	v_and_or_b32 v80, v80, s58, v79
	v_bfe_u32 v79, v82, 16, 1
	v_add3_u32 v79, v82, v79, s8
	v_bfe_u32 v81, v83, 16, 1
	v_lshrrev_b32_e32 v79, 16, v79
	v_add3_u32 v81, v83, v81, s8
	v_and_or_b32 v81, v81, s58, v79
	global_store_dwordx2 v[76:77], v[80:81], off offset:-2048
	v_pk_mul_f32 v[80:81], v[106:107], v[78:79] op_sel_hi:[1,0]
	v_pk_mul_f32 v[82:83], v[104:105], v[78:79] op_sel_hi:[1,0]
	v_pk_fma_f32 v[80:81], v[52:53], v[80:81], v[18:19]
	v_pk_fma_f32 v[82:83], v[50:51], v[82:83], v[20:21]
	v_bfe_u32 v79, v80, 16, 1
	v_add3_u32 v79, v80, v79, s8
	v_bfe_u32 v80, v81, 16, 1
	v_lshrrev_b32_e32 v79, 16, v79
	v_add3_u32 v80, v81, v80, s8
	v_and_or_b32 v80, v80, s58, v79
	v_bfe_u32 v79, v82, 16, 1
	v_add3_u32 v79, v82, v79, s8
	v_bfe_u32 v81, v83, 16, 1
	v_lshrrev_b32_e32 v79, 16, v79
	v_add3_u32 v81, v83, v81, s8
	v_and_or_b32 v81, v81, s58, v79
	global_store_dwordx2 v[76:77], v[80:81], off offset:-1536
	v_pk_mul_f32 v[80:81], v[108:109], v[78:79] op_sel_hi:[1,0]
	v_pk_mul_f32 v[82:83], v[110:111], v[78:79] op_sel_hi:[1,0]
	v_pk_fma_f32 v[80:81], v[56:57], v[80:81], v[22:23]
	v_pk_fma_f32 v[82:83], v[54:55], v[82:83], v[24:25]
	v_bfe_u32 v79, v80, 16, 1
	v_add3_u32 v79, v80, v79, s8
	v_bfe_u32 v80, v81, 16, 1
	v_lshrrev_b32_e32 v79, 16, v79
	v_add3_u32 v80, v81, v80, s8
	v_and_or_b32 v80, v80, s58, v79
	v_bfe_u32 v79, v82, 16, 1
	v_add3_u32 v79, v82, v79, s8
	v_bfe_u32 v81, v83, 16, 1
	v_lshrrev_b32_e32 v79, 16, v79
	v_add3_u32 v81, v83, v81, s8
	v_and_or_b32 v81, v81, s58, v79
	global_store_dwordx2 v[76:77], v[80:81], off offset:-1024
	v_pk_mul_f32 v[80:81], v[96:97], v[78:79] op_sel_hi:[1,0]
	v_pk_mul_f32 v[82:83], v[98:99], v[78:79] op_sel_hi:[1,0]
	v_pk_fma_f32 v[80:81], v[60:61], v[80:81], v[26:27]
	v_pk_fma_f32 v[82:83], v[58:59], v[82:83], v[28:29]
	v_bfe_u32 v79, v80, 16, 1
	v_add3_u32 v79, v80, v79, s8
	v_bfe_u32 v80, v81, 16, 1
	v_lshrrev_b32_e32 v79, 16, v79
	v_add3_u32 v80, v81, v80, s8
	v_and_or_b32 v80, v80, s58, v79
	v_bfe_u32 v79, v82, 16, 1
	v_add3_u32 v79, v82, v79, s8
	v_bfe_u32 v81, v83, 16, 1
	v_lshrrev_b32_e32 v79, 16, v79
	v_add3_u32 v81, v83, v81, s8
	v_and_or_b32 v81, v81, s58, v79
	global_store_dwordx2 v[76:77], v[80:81], off offset:-512
	v_pk_mul_f32 v[80:81], v[88:89], v[78:79] op_sel_hi:[1,0]
	v_pk_mul_f32 v[78:79], v[90:91], v[78:79] op_sel_hi:[1,0]
	v_pk_fma_f32 v[80:81], v[64:65], v[80:81], v[30:31]
	v_pk_fma_f32 v[78:79], v[62:63], v[78:79], v[32:33]
	v_bfe_u32 v82, v80, 16, 1
	v_add3_u32 v80, v80, v82, s8
	v_bfe_u32 v82, v81, 16, 1
	v_lshrrev_b32_e32 v80, 16, v80
	v_add3_u32 v81, v81, v82, s8
	v_and_or_b32 v80, v81, s58, v80
	v_bfe_u32 v81, v78, 16, 1
	v_add3_u32 v78, v78, v81, s8
	v_bfe_u32 v81, v79, 16, 1
	v_lshrrev_b32_e32 v78, 16, v78
	v_add3_u32 v79, v79, v81, s8
	v_and_or_b32 v81, v79, s58, v78
	global_store_dwordx2 v[76:77], v[80:81], off
	v_lshl_add_u64 v[76:77], v[76:77], 0, s[90:91]
	s_cbranch_scc1 .LBB9_1724
